# M1c rewrite with safe vmcnt(0) waits (mixed-width loads complete out of order); M4' waits made conservative
# baseline (speedup 1.0000x reference)
; DI float gelu_f(float x) { return x * __builtin_amdgcn_rcpf(1.f + __builtin_amdgcn_exp2f(x * (-2.302208198f + -0.102943240f * (x * x)))); }
; __global__ void __launch_bounds__(512, 2) fwd_megakernel(Args args) {
;     ...
;                 const int l = tid >> 2, sub = tid & 3;
;                 u32x4 gvr[8], ur[8]; bf16x8 wa[4][4];
;                 {
;                     const bf16* src = proj + (grow0 + l) * NPROJ + PC_GV + sub * 64;
; #pragma unroll
;                     for (int k = 0; k < 8; ++k) gvr[k] = *(const u32x4*)(src + 8 * k);
; #pragma unroll
;                     for (int k = 0; k < 8; ++k) { const int it = tid + 512 * k, t = it >> 5, c8 = (it & 31) * 8; ur[k] = *(const u32x4*)(proj + (grow0 + t) * NPROJ + PC_U + c8); }
;                 }
;                 {
;                     float v[64]; float sm = 0.f;
; #pragma unroll
;                     for (int k = 0; k < 8; ++k) { float t8[8]; unpack8(gvr[k], t8);
; #pragma unroll
;                         for (int i = 0; i < 8; ++i) { v[8 * k + i] = gelu_f(t8[i]); sm += v[8 * k + i]; } }
.LBB0_800:
	s_waitcnt vmcnt(0) lgkmcnt(0)
	v_readlane_b32 s2, v252, 0
	s_and_b32 s3, s54, 7
	s_lshl_b32 s3, s3, 5
	s_lshr_b32 s4, s54, 3
	s_add_i32 s3, s3, s4
	s_mul_i32 s4, s3, 0xb0000
	s_add_u32 s8, s80, 0x15000000
	s_addc_u32 s9, s81, 0
	s_add_u32 s8, s8, s4
	s_addc_u32 s9, s9, 0
	s_lshl_b32 s4, s3, 18
	s_add_u32 s10, s80, 0xe000600
	s_addc_u32 s11, s81, 0
	s_add_u32 s10, s10, s4
	s_addc_u32 s11, s11, 0
	v_readlane_b32 s5, v253, 58
	s_lshl_b32 s6, s5, 14
	s_add_u32 s12, s80, 0x600000
	s_addc_u32 s13, s81, 0
	s_add_u32 s12, s12, s6
	s_addc_u32 s13, s13, 0
	s_lshl_b32 s6, s5, 7
	v_readlane_b32 s14, v251, 41
	v_readlane_b32 s15, v251, 42
	s_add_u32 s14, s14, s6
	s_addc_u32 s15, s15, 0
	v_readlane_b32 s22, v251, 43
	v_readlane_b32 s23, v251, 44
	s_add_u32 s22, s22, s6
	s_addc_u32 s23, s23, 0
	v_readlane_b32 s24, v251, 49
	v_readlane_b32 s25, v251, 50
	s_add_u32 s24, s24, s6
	s_addc_u32 s25, s25, 0
	s_lshl_b32 s6, s5, 8
	v_readlane_b32 s36, v251, 47
	v_readlane_b32 s37, v251, 48
	s_add_u32 s36, s36, s6
	s_addc_u32 s37, s37, 0
	v_and_b32_e32 v184, 63, v195
	v_and_b32_e32 v185, 15, v184
	v_lshrrev_b32_e32 v186, 4, v184
	v_lshl_add_u32 v187, s2, 4, v185
	v_lshlrev_b32_e32 v196, 2, v186
	v_lshl_add_u32 v196, s2, 4, v196
	v_mul_u32_u24_e32 v188, 0x1600, v196
	v_lshl_add_u32 v188, v185, 5, v188
	v_add_u32_e32 v188, 0x1200, v188
	global_load_dwordx4 v[0:3], v188, s[8:9]
	global_load_dwordx4 v[4:7], v188, s[8:9] offset:16
	v_add_u32_e32 v188, 0x1600, v188
	global_load_dwordx4 v[8:11], v188, s[8:9]
	global_load_dwordx4 v[12:15], v188, s[8:9] offset:16
	v_add_u32_e32 v188, 0x1600, v188
	global_load_dwordx4 v[16:19], v188, s[8:9]
	global_load_dwordx4 v[20:23], v188, s[8:9] offset:16
	v_add_u32_e32 v188, 0x1600, v188
	global_load_dwordx4 v[24:27], v188, s[8:9]
	global_load_dwordx4 v[28:31], v188, s[8:9] offset:16
	v_lshlrev_b32_e32 v188, 6, v185
	global_load_dwordx4 v[32:35], v188, s[14:15] offset:0
	global_load_dwordx4 v[48:51], v188, s[22:23] offset:0
	global_load_dwordx4 v[36:39], v188, s[14:15] offset:16
	global_load_dwordx4 v[52:55], v188, s[22:23] offset:16
	global_load_dwordx4 v[40:43], v188, s[14:15] offset:32
	global_load_dwordx4 v[56:59], v188, s[22:23] offset:32
	global_load_dwordx4 v[44:47], v188, s[14:15] offset:48
	global_load_dwordx4 v[60:63], v188, s[22:23] offset:48
	v_mul_u32_u24_e32 v188, 0x1600, v187
	v_lshl_add_u32 v188, v186, 3, v188
	v_add_u32_e32 v188, 0x1000, v188
	global_load_dwordx2 v[148:149], v188, s[8:9] offset:0
	global_load_dwordx2 v[150:151], v188, s[8:9] offset:32
	global_load_dwordx2 v[152:153], v188, s[8:9] offset:64
	global_load_dwordx2 v[154:155], v188, s[8:9] offset:96
	global_load_dwordx2 v[156:157], v188, s[8:9] offset:128
	global_load_dwordx2 v[158:159], v188, s[8:9] offset:160
	global_load_dwordx2 v[160:161], v188, s[8:9] offset:192
	global_load_dwordx2 v[162:163], v188, s[8:9] offset:224
	global_load_dwordx2 v[164:165], v188, s[8:9] offset:256
	global_load_dwordx2 v[166:167], v188, s[8:9] offset:288
	global_load_dwordx2 v[168:169], v188, s[8:9] offset:320
	global_load_dwordx2 v[170:171], v188, s[8:9] offset:352
	global_load_dwordx2 v[172:173], v188, s[8:9] offset:384
	global_load_dwordx2 v[174:175], v188, s[8:9] offset:416
	global_load_dwordx2 v[176:177], v188, s[8:9] offset:448
	global_load_dwordx2 v[178:179], v188, s[8:9] offset:480
	v_lshlrev_b32_e32 v188, 2, v187
	global_load_dword v180, v188, s[36:37] offset:0
	global_load_dword v181, v188, s[36:37] offset:512
	global_load_dword v182, v188, s[36:37] offset:1024
	global_load_dword v183, v188, s[36:37] offset:1536
	v_lshrrev_b32_e32 v189, 2, v185
	v_mul_u32_u24_e32 v189, 0x4400, v189
	v_and_b32_e32 v188, 3, v185
	v_mul_u32_u24_e32 v188, 0x1100, v188
	v_add_u32_e32 v189, v189, v188
	v_lshl_add_u32 v189, v196, 1, v189
	v_mov_b32_e32 v190, 0xc0135761
	v_mov_b32_e32 v191, 0xbdd2d3e8
	s_waitcnt vmcnt(0)
	v_lshlrev_b32_e32 v64, 16, v0
	v_and_b32_e32 v65, 0xffff0000, v0
	v_lshlrev_b32_e32 v66, 16, v1
	v_and_b32_e32 v67, 0xffff0000, v1
	v_lshlrev_b32_e32 v68, 16, v2
	v_and_b32_e32 v69, 0xffff0000, v2
	v_lshlrev_b32_e32 v70, 16, v3
	v_and_b32_e32 v71, 0xffff0000, v3
	v_lshlrev_b32_e32 v72, 16, v4
	v_and_b32_e32 v73, 0xffff0000, v4
	v_lshlrev_b32_e32 v74, 16, v5
	v_and_b32_e32 v75, 0xffff0000, v5
	v_lshlrev_b32_e32 v76, 16, v6
	v_and_b32_e32 v77, 0xffff0000, v6
	v_lshlrev_b32_e32 v78, 16, v7
	v_and_b32_e32 v79, 0xffff0000, v7
	v_mul_f32_e32 v132, v64, v64
	v_mul_f32_e32 v133, v65, v65
	v_mul_f32_e32 v134, v66, v66
	v_mul_f32_e32 v135, v67, v67
	v_mul_f32_e32 v136, v68, v68
	v_mul_f32_e32 v137, v69, v69
	v_mul_f32_e32 v138, v70, v70
	v_mul_f32_e32 v139, v71, v71
	v_mul_f32_e32 v140, v72, v72
	v_mul_f32_e32 v141, v73, v73
	v_mul_f32_e32 v142, v74, v74
	v_mul_f32_e32 v143, v75, v75
	v_mul_f32_e32 v144, v76, v76
	v_mul_f32_e32 v145, v77, v77
	v_mul_f32_e32 v146, v78, v78
	v_mul_f32_e32 v147, v79, v79
	v_fma_f32 v132, v132, v191, v190
	v_fma_f32 v133, v133, v191, v190
	v_fma_f32 v134, v134, v191, v190
	v_fma_f32 v135, v135, v191, v190
	v_fma_f32 v136, v136, v191, v190
	v_fma_f32 v137, v137, v191, v190
	v_fma_f32 v138, v138, v191, v190
	v_fma_f32 v139, v139, v191, v190
	v_fma_f32 v140, v140, v191, v190
	v_fma_f32 v141, v141, v191, v190
	v_fma_f32 v142, v142, v191, v190
	v_fma_f32 v143, v143, v191, v190
	v_fma_f32 v144, v144, v191, v190
	v_fma_f32 v145, v145, v191, v190
	v_fma_f32 v146, v146, v191, v190
	v_fma_f32 v147, v147, v191, v190
	v_mul_f32_e32 v132, v132, v64
	v_mul_f32_e32 v133, v133, v65
	v_mul_f32_e32 v134, v134, v66
	v_mul_f32_e32 v135, v135, v67
	v_mul_f32_e32 v136, v136, v68
	v_mul_f32_e32 v137, v137, v69
	v_mul_f32_e32 v138, v138, v70
	v_mul_f32_e32 v139, v139, v71
; #define LAS __attribute__((address_space(3)))
; DI unsigned short f2bf(float f) { return (unsigned short)(pk2(f, 0.f) & 0xffffu); }
; DI float gelu_f(float x) { return x * __builtin_amdgcn_rcpf(1.f + __builtin_amdgcn_exp2f(x * (-2.302208198f + -0.102943240f * (x * x)))); }
; __global__ void __launch_bounds__(512, 2) fwd_megakernel(Args args) {
;     ...
;                     float v[64]; float sm = 0.f;
; #pragma unroll
;                     for (int k = 0; k < 8; ++k) { float t8[8]; unpack8(gvr[k], t8);
; #pragma unroll
;                         for (int i = 0; i < 8; ++i) { v[8 * k + i] = gelu_f(t8[i]); sm += v[8 * k + i]; } }
;                     sm += __shfl_xor(sm, 1); sm += __shfl_xor(sm, 2);
;                     const float mean = sm * (1.f / 256.f); float qv = 0.f;
; #pragma unroll
;                     for (int i = 0; i < 64; ++i) { const float d = v[i] - mean; qv += d * d; }
;                     qv += __shfl_xor(qv, 1); qv += __shfl_xor(qv, 2);
;                     const float rstd = rsqrtf(qv * (1.f / 256.f) + EPS);
;                     const float* lw = args.in[16] + layer * 256 + sub * 64; const float* lb = args.in[17] + layer * 256 + sub * 64;
;                     LAS bf16* dst = vnT + sub * (64 * 136) + l;
; #pragma unroll
;                     for (int i = 0; i < 64; ++i) dst[i * 136] = f2bf((v[i] - mean) * rstd * lw[i] + lb[i]);
	v_mul_f32_e32 v140, v140, v72
	v_mul_f32_e32 v141, v141, v73
	v_mul_f32_e32 v142, v142, v74
	v_mul_f32_e32 v143, v143, v75
	v_mul_f32_e32 v144, v144, v76
	v_mul_f32_e32 v145, v145, v77
	v_mul_f32_e32 v146, v146, v78
	v_mul_f32_e32 v147, v147, v79
	v_exp_f32_e32 v132, v132
	v_exp_f32_e32 v133, v133
	v_exp_f32_e32 v134, v134
	v_exp_f32_e32 v135, v135
	v_exp_f32_e32 v136, v136
	v_exp_f32_e32 v137, v137
	v_exp_f32_e32 v138, v138
	v_exp_f32_e32 v139, v139
	v_exp_f32_e32 v140, v140
	v_exp_f32_e32 v141, v141
	v_exp_f32_e32 v142, v142
	v_exp_f32_e32 v143, v143
	v_exp_f32_e32 v144, v144
	v_exp_f32_e32 v145, v145
	v_exp_f32_e32 v146, v146
	v_exp_f32_e32 v147, v147
	s_nop 0
	v_add_f32_e32 v132, 1.0, v132
	v_add_f32_e32 v133, 1.0, v133
	v_add_f32_e32 v134, 1.0, v134
	v_add_f32_e32 v135, 1.0, v135
	v_add_f32_e32 v136, 1.0, v136
	v_add_f32_e32 v137, 1.0, v137
	v_add_f32_e32 v138, 1.0, v138
	v_add_f32_e32 v139, 1.0, v139
	v_add_f32_e32 v140, 1.0, v140
	v_add_f32_e32 v141, 1.0, v141
	v_add_f32_e32 v142, 1.0, v142
	v_add_f32_e32 v143, 1.0, v143
	v_add_f32_e32 v144, 1.0, v144
	v_add_f32_e32 v145, 1.0, v145
	v_add_f32_e32 v146, 1.0, v146
	v_add_f32_e32 v147, 1.0, v147
	v_rcp_f32_e32 v132, v132
	v_rcp_f32_e32 v133, v133
	v_rcp_f32_e32 v134, v134
	v_rcp_f32_e32 v135, v135
	v_rcp_f32_e32 v136, v136
	v_rcp_f32_e32 v137, v137
	v_rcp_f32_e32 v138, v138
	v_rcp_f32_e32 v139, v139
	v_rcp_f32_e32 v140, v140
	v_rcp_f32_e32 v141, v141
	v_rcp_f32_e32 v142, v142
	v_rcp_f32_e32 v143, v143
	v_rcp_f32_e32 v144, v144
	v_rcp_f32_e32 v145, v145
	v_rcp_f32_e32 v146, v146
	v_rcp_f32_e32 v147, v147
	s_nop 0
	v_mul_f32_e32 v64, v64, v132
	v_mul_f32_e32 v65, v65, v133
	v_mul_f32_e32 v66, v66, v134
	v_mul_f32_e32 v67, v67, v135
	v_mul_f32_e32 v68, v68, v136
	v_mul_f32_e32 v69, v69, v137
	v_mul_f32_e32 v70, v70, v138
	v_mul_f32_e32 v71, v71, v139
	v_mul_f32_e32 v72, v72, v140
	v_mul_f32_e32 v73, v73, v141
	v_mul_f32_e32 v74, v74, v142
	v_mul_f32_e32 v75, v75, v143
	v_mul_f32_e32 v76, v76, v144
	v_mul_f32_e32 v77, v77, v145
	v_mul_f32_e32 v78, v78, v146
	v_mul_f32_e32 v79, v79, v147
	v_add_f32_e32 v132, v64, v65
	v_add_f32_e32 v132, v132, v66
	v_add_f32_e32 v132, v132, v67
	v_add_f32_e32 v132, v132, v68
	v_add_f32_e32 v132, v132, v69
	v_add_f32_e32 v132, v132, v70
	v_add_f32_e32 v132, v132, v71
	v_add_f32_e32 v132, v132, v72
	v_add_f32_e32 v132, v132, v73
	v_add_f32_e32 v132, v132, v74
	v_add_f32_e32 v132, v132, v75
	v_add_f32_e32 v132, v132, v76
	v_add_f32_e32 v132, v132, v77
	v_add_f32_e32 v132, v132, v78
	v_add_f32_e32 v132, v132, v79
	s_nop 1
	v_add_f32_dpp v132, v132, v132 quad_perm:[1,0,3,2] row_mask:0xf bank_mask:0xf
	s_nop 1
	v_add_f32_dpp v132, v132, v132 quad_perm:[2,3,0,1] row_mask:0xf bank_mask:0xf
	s_nop 1
	v_add_f32_dpp v132, v132, v132 row_half_mirror row_mask:0xf bank_mask:0xf
	s_nop 1
	v_add_f32_dpp v132, v132, v132 row_mirror row_mask:0xf bank_mask:0xf
	s_nop 1
	v_mul_f32_e32 v132, 0x3b800000, v132
	v_sub_f32_e32 v64, v64, v132
	v_sub_f32_e32 v65, v65, v132
	v_sub_f32_e32 v66, v66, v132
	v_sub_f32_e32 v67, v67, v132
	v_sub_f32_e32 v68, v68, v132
	v_sub_f32_e32 v69, v69, v132
	v_sub_f32_e32 v70, v70, v132
	v_sub_f32_e32 v71, v71, v132
	v_sub_f32_e32 v72, v72, v132
	v_sub_f32_e32 v73, v73, v132
	v_sub_f32_e32 v74, v74, v132
	v_sub_f32_e32 v75, v75, v132
	v_sub_f32_e32 v76, v76, v132
	v_sub_f32_e32 v77, v77, v132
	v_sub_f32_e32 v78, v78, v132
	v_sub_f32_e32 v79, v79, v132
	v_mul_f32_e32 v133, v64, v64
	v_fmac_f32_e32 v133, v65, v65
	v_fmac_f32_e32 v133, v66, v66
	v_fmac_f32_e32 v133, v67, v67
	v_fmac_f32_e32 v133, v68, v68
	v_fmac_f32_e32 v133, v69, v69
	v_fmac_f32_e32 v133, v70, v70
	v_fmac_f32_e32 v133, v71, v71
	v_fmac_f32_e32 v133, v72, v72
	v_fmac_f32_e32 v133, v73, v73
	v_fmac_f32_e32 v133, v74, v74
	v_fmac_f32_e32 v133, v75, v75
	v_fmac_f32_e32 v133, v76, v76
	v_fmac_f32_e32 v133, v77, v77
	v_fmac_f32_e32 v133, v78, v78
	v_fmac_f32_e32 v133, v79, v79
	s_nop 1
	v_add_f32_dpp v133, v133, v133 quad_perm:[1,0,3,2] row_mask:0xf bank_mask:0xf
	s_nop 1
	v_add_f32_dpp v133, v133, v133 quad_perm:[2,3,0,1] row_mask:0xf bank_mask:0xf
	s_nop 1
	v_add_f32_dpp v133, v133, v133 row_half_mirror row_mask:0xf bank_mask:0xf
	s_nop 1
	v_add_f32_dpp v133, v133, v133 row_mirror row_mask:0xf bank_mask:0xf
	s_nop 1
	v_mov_b32_e32 v134, 0x358637bd
	v_fmamk_f32 v133, v133, 0x3b800000, v134
	v_rsq_f32_e32 v133, v133
	s_nop 0
	v_mul_f32_e32 v64, v64, v133
	v_mul_f32_e32 v65, v65, v133
	v_mul_f32_e32 v66, v66, v133
	v_mul_f32_e32 v67, v67, v133
	v_mul_f32_e32 v68, v68, v133
	v_mul_f32_e32 v69, v69, v133
	v_mul_f32_e32 v70, v70, v133
	v_mul_f32_e32 v71, v71, v133
	v_mul_f32_e32 v72, v72, v133
	v_mul_f32_e32 v73, v73, v133
	v_mul_f32_e32 v74, v74, v133
	v_mul_f32_e32 v75, v75, v133
	v_mul_f32_e32 v76, v76, v133
	v_mul_f32_e32 v77, v77, v133
	v_mul_f32_e32 v78, v78, v133
	v_mul_f32_e32 v79, v79, v133
	v_fma_f32 v64, v64, v32, v48
	v_fma_f32 v65, v65, v33, v49
	v_fma_f32 v66, v66, v34, v50
	v_fma_f32 v67, v67, v35, v51
	v_fma_f32 v68, v68, v36, v52
	v_fma_f32 v69, v69, v37, v53
	v_fma_f32 v70, v70, v38, v54
	v_fma_f32 v71, v71, v39, v55
	v_fma_f32 v72, v72, v40, v56
	v_fma_f32 v73, v73, v41, v57
	v_fma_f32 v74, v74, v42, v58
	v_fma_f32 v75, v75, v43, v59
	v_fma_f32 v76, v76, v44, v60
	v_fma_f32 v77, v77, v45, v61
	v_fma_f32 v78, v78, v46, v62
	v_fma_f32 v79, v79, v47, v63
	v_lshlrev_b32_e32 v80, 16, v8
	v_and_b32_e32 v81, 0xffff0000, v8
	v_lshlrev_b32_e32 v82, 16, v9
	v_and_b32_e32 v83, 0xffff0000, v9
	v_lshlrev_b32_e32 v84, 16, v10
	v_and_b32_e32 v85, 0xffff0000, v10
	v_lshlrev_b32_e32 v86, 16, v11
	v_and_b32_e32 v87, 0xffff0000, v11
	v_lshlrev_b32_e32 v92, 16, v12
	v_and_b32_e32 v93, 0xffff0000, v12
; #define LAS __attribute__((address_space(3)))
; DI unsigned short f2bf(float f) { return (unsigned short)(pk2(f, 0.f) & 0xffffu); }
; DI float gelu_f(float x) { return x * __builtin_amdgcn_rcpf(1.f + __builtin_amdgcn_exp2f(x * (-2.302208198f + -0.102943240f * (x * x)))); }
; __global__ void __launch_bounds__(512, 2) fwd_megakernel(Args args) {
;     ...
;                     float v[64]; float sm = 0.f;
; #pragma unroll
;                     for (int k = 0; k < 8; ++k) { float t8[8]; unpack8(gvr[k], t8);
; #pragma unroll
;                         for (int i = 0; i < 8; ++i) { v[8 * k + i] = gelu_f(t8[i]); sm += v[8 * k + i]; } }
;                     sm += __shfl_xor(sm, 1); sm += __shfl_xor(sm, 2);
;                     const float mean = sm * (1.f / 256.f); float qv = 0.f;
; #pragma unroll
;                     for (int i = 0; i < 64; ++i) { const float d = v[i] - mean; qv += d * d; }
;                     qv += __shfl_xor(qv, 1); qv += __shfl_xor(qv, 2);
;                     const float rstd = rsqrtf(qv * (1.f / 256.f) + EPS);
;                     const float* lw = args.in[16] + layer * 256 + sub * 64; const float* lb = args.in[17] + layer * 256 + sub * 64;
;                     LAS bf16* dst = vnT + sub * (64 * 136) + l;
; #pragma unroll
;                     for (int i = 0; i < 64; ++i) dst[i * 136] = f2bf((v[i] - mean) * rstd * lw[i] + lb[i]);
	v_lshlrev_b32_e32 v94, 16, v13
	v_and_b32_e32 v95, 0xffff0000, v13
	v_lshlrev_b32_e32 v96, 16, v14
	v_and_b32_e32 v97, 0xffff0000, v14
	v_lshlrev_b32_e32 v98, 16, v15
	v_and_b32_e32 v99, 0xffff0000, v15
	v_mul_f32_e32 v132, v80, v80
	v_mul_f32_e32 v133, v81, v81
	v_mul_f32_e32 v134, v82, v82
	v_mul_f32_e32 v135, v83, v83
	v_mul_f32_e32 v136, v84, v84
	v_mul_f32_e32 v137, v85, v85
	v_mul_f32_e32 v138, v86, v86
	v_mul_f32_e32 v139, v87, v87
	v_mul_f32_e32 v140, v92, v92
	v_mul_f32_e32 v141, v93, v93
	v_mul_f32_e32 v142, v94, v94
	v_mul_f32_e32 v143, v95, v95
	v_mul_f32_e32 v144, v96, v96
	v_mul_f32_e32 v145, v97, v97
	v_mul_f32_e32 v146, v98, v98
	v_mul_f32_e32 v147, v99, v99
	v_fma_f32 v132, v132, v191, v190
	v_fma_f32 v133, v133, v191, v190
	v_fma_f32 v134, v134, v191, v190
	v_fma_f32 v135, v135, v191, v190
	v_fma_f32 v136, v136, v191, v190
	v_fma_f32 v137, v137, v191, v190
	v_fma_f32 v138, v138, v191, v190
	v_fma_f32 v139, v139, v191, v190
	v_fma_f32 v140, v140, v191, v190
	v_fma_f32 v141, v141, v191, v190
	v_fma_f32 v142, v142, v191, v190
	v_fma_f32 v143, v143, v191, v190
	v_fma_f32 v144, v144, v191, v190
	v_fma_f32 v145, v145, v191, v190
	v_fma_f32 v146, v146, v191, v190
	v_fma_f32 v147, v147, v191, v190
	v_mul_f32_e32 v132, v132, v80
	v_mul_f32_e32 v133, v133, v81
	v_mul_f32_e32 v134, v134, v82
	v_mul_f32_e32 v135, v135, v83
	v_mul_f32_e32 v136, v136, v84
	v_mul_f32_e32 v137, v137, v85
	v_mul_f32_e32 v138, v138, v86
	v_mul_f32_e32 v139, v139, v87
	v_mul_f32_e32 v140, v140, v92
	v_mul_f32_e32 v141, v141, v93
	v_mul_f32_e32 v142, v142, v94
	v_mul_f32_e32 v143, v143, v95
	v_mul_f32_e32 v144, v144, v96
	v_mul_f32_e32 v145, v145, v97
	v_mul_f32_e32 v146, v146, v98
	v_mul_f32_e32 v147, v147, v99
	v_exp_f32_e32 v132, v132
	v_exp_f32_e32 v133, v133
	v_exp_f32_e32 v134, v134
	v_exp_f32_e32 v135, v135
	v_exp_f32_e32 v136, v136
	v_exp_f32_e32 v137, v137
	v_exp_f32_e32 v138, v138
	v_exp_f32_e32 v139, v139
	v_exp_f32_e32 v140, v140
	v_exp_f32_e32 v141, v141
	v_exp_f32_e32 v142, v142
	v_exp_f32_e32 v143, v143
	v_exp_f32_e32 v144, v144
	v_exp_f32_e32 v145, v145
	v_exp_f32_e32 v146, v146
	v_exp_f32_e32 v147, v147
	s_nop 0
	v_add_f32_e32 v132, 1.0, v132
	v_add_f32_e32 v133, 1.0, v133
	v_add_f32_e32 v134, 1.0, v134
	v_add_f32_e32 v135, 1.0, v135
	v_add_f32_e32 v136, 1.0, v136
	v_add_f32_e32 v137, 1.0, v137
	v_add_f32_e32 v138, 1.0, v138
	v_add_f32_e32 v139, 1.0, v139
	v_add_f32_e32 v140, 1.0, v140
	v_add_f32_e32 v141, 1.0, v141
	v_add_f32_e32 v142, 1.0, v142
	v_add_f32_e32 v143, 1.0, v143
	v_add_f32_e32 v144, 1.0, v144
	v_add_f32_e32 v145, 1.0, v145
	v_add_f32_e32 v146, 1.0, v146
	v_add_f32_e32 v147, 1.0, v147
	v_rcp_f32_e32 v132, v132
	v_rcp_f32_e32 v133, v133
	v_rcp_f32_e32 v134, v134
	v_rcp_f32_e32 v135, v135
	v_rcp_f32_e32 v136, v136
	v_rcp_f32_e32 v137, v137
	v_rcp_f32_e32 v138, v138
	v_rcp_f32_e32 v139, v139
	v_rcp_f32_e32 v140, v140
	v_rcp_f32_e32 v141, v141
	v_rcp_f32_e32 v142, v142
	v_rcp_f32_e32 v143, v143
	v_rcp_f32_e32 v144, v144
	v_rcp_f32_e32 v145, v145
	v_rcp_f32_e32 v146, v146
	v_rcp_f32_e32 v147, v147
	s_nop 0
	v_mul_f32_e32 v80, v80, v132
	v_mul_f32_e32 v81, v81, v133
	v_mul_f32_e32 v82, v82, v134
	v_mul_f32_e32 v83, v83, v135
	v_mul_f32_e32 v84, v84, v136
	v_mul_f32_e32 v85, v85, v137
	v_mul_f32_e32 v86, v86, v138
	v_mul_f32_e32 v87, v87, v139
	v_mul_f32_e32 v92, v92, v140
	v_mul_f32_e32 v93, v93, v141
	v_mul_f32_e32 v94, v94, v142
	v_mul_f32_e32 v95, v95, v143
	v_mul_f32_e32 v96, v96, v144
	v_mul_f32_e32 v97, v97, v145
	v_mul_f32_e32 v98, v98, v146
	v_mul_f32_e32 v99, v99, v147
	v_add_f32_e32 v132, v80, v81
	v_add_f32_e32 v132, v132, v82
	v_add_f32_e32 v132, v132, v83
	v_add_f32_e32 v132, v132, v84
	v_add_f32_e32 v132, v132, v85
	v_add_f32_e32 v132, v132, v86
	v_add_f32_e32 v132, v132, v87
	v_add_f32_e32 v132, v132, v92
	v_add_f32_e32 v132, v132, v93
	v_add_f32_e32 v132, v132, v94
	v_add_f32_e32 v132, v132, v95
	v_add_f32_e32 v132, v132, v96
	v_add_f32_e32 v132, v132, v97
	v_add_f32_e32 v132, v132, v98
	v_add_f32_e32 v132, v132, v99
	s_nop 1
	v_add_f32_dpp v132, v132, v132 quad_perm:[1,0,3,2] row_mask:0xf bank_mask:0xf
	s_nop 1
	v_add_f32_dpp v132, v132, v132 quad_perm:[2,3,0,1] row_mask:0xf bank_mask:0xf
	s_nop 1
	v_add_f32_dpp v132, v132, v132 row_half_mirror row_mask:0xf bank_mask:0xf
	s_nop 1
	v_add_f32_dpp v132, v132, v132 row_mirror row_mask:0xf bank_mask:0xf
	s_nop 1
	v_mul_f32_e32 v132, 0x3b800000, v132
	v_sub_f32_e32 v80, v80, v132
	v_sub_f32_e32 v81, v81, v132
	v_sub_f32_e32 v82, v82, v132
	v_sub_f32_e32 v83, v83, v132
	v_sub_f32_e32 v84, v84, v132
	v_sub_f32_e32 v85, v85, v132
	v_sub_f32_e32 v86, v86, v132
	v_sub_f32_e32 v87, v87, v132
	v_sub_f32_e32 v92, v92, v132
	v_sub_f32_e32 v93, v93, v132
	v_sub_f32_e32 v94, v94, v132
	v_sub_f32_e32 v95, v95, v132
	v_sub_f32_e32 v96, v96, v132
	v_sub_f32_e32 v97, v97, v132
	v_sub_f32_e32 v98, v98, v132
	v_sub_f32_e32 v99, v99, v132
	v_mul_f32_e32 v133, v80, v80
	v_fmac_f32_e32 v133, v81, v81
	v_fmac_f32_e32 v133, v82, v82
	v_fmac_f32_e32 v133, v83, v83
	v_fmac_f32_e32 v133, v84, v84
	v_fmac_f32_e32 v133, v85, v85
	v_fmac_f32_e32 v133, v86, v86
	v_fmac_f32_e32 v133, v87, v87
	v_fmac_f32_e32 v133, v92, v92
	v_fmac_f32_e32 v133, v93, v93
	v_fmac_f32_e32 v133, v94, v94
	v_fmac_f32_e32 v133, v95, v95
	v_fmac_f32_e32 v133, v96, v96
	v_fmac_f32_e32 v133, v97, v97
	v_fmac_f32_e32 v133, v98, v98
	v_fmac_f32_e32 v133, v99, v99
	s_nop 1
	v_add_f32_dpp v133, v133, v133 quad_perm:[1,0,3,2] row_mask:0xf bank_mask:0xf
	s_nop 1
	v_add_f32_dpp v133, v133, v133 quad_perm:[2,3,0,1] row_mask:0xf bank_mask:0xf
	s_nop 1
	v_add_f32_dpp v133, v133, v133 row_half_mirror row_mask:0xf bank_mask:0xf
	s_nop 1
; #define LAS __attribute__((address_space(3)))
; DI unsigned short f2bf(float f) { return (unsigned short)(pk2(f, 0.f) & 0xffffu); }
; DI float gelu_f(float x) { return x * __builtin_amdgcn_rcpf(1.f + __builtin_amdgcn_exp2f(x * (-2.302208198f + -0.102943240f * (x * x)))); }
; __global__ void __launch_bounds__(512, 2) fwd_megakernel(Args args) {
;     ...
;                     float v[64]; float sm = 0.f;
; #pragma unroll
;                     for (int k = 0; k < 8; ++k) { float t8[8]; unpack8(gvr[k], t8);
; #pragma unroll
;                         for (int i = 0; i < 8; ++i) { v[8 * k + i] = gelu_f(t8[i]); sm += v[8 * k + i]; } }
;                     sm += __shfl_xor(sm, 1); sm += __shfl_xor(sm, 2);
;                     const float mean = sm * (1.f / 256.f); float qv = 0.f;
; #pragma unroll
;                     for (int i = 0; i < 64; ++i) { const float d = v[i] - mean; qv += d * d; }
;                     qv += __shfl_xor(qv, 1); qv += __shfl_xor(qv, 2);
;                     const float rstd = rsqrtf(qv * (1.f / 256.f) + EPS);
;                     const float* lw = args.in[16] + layer * 256 + sub * 64; const float* lb = args.in[17] + layer * 256 + sub * 64;
;                     LAS bf16* dst = vnT + sub * (64 * 136) + l;
; #pragma unroll
;                     for (int i = 0; i < 64; ++i) dst[i * 136] = f2bf((v[i] - mean) * rstd * lw[i] + lb[i]);
	v_add_f32_dpp v133, v133, v133 row_mirror row_mask:0xf bank_mask:0xf
	s_nop 1
	v_mov_b32_e32 v134, 0x358637bd
	v_fmamk_f32 v133, v133, 0x3b800000, v134
	v_rsq_f32_e32 v133, v133
	s_nop 0
	v_mul_f32_e32 v80, v80, v133
	v_mul_f32_e32 v81, v81, v133
	v_mul_f32_e32 v82, v82, v133
	v_mul_f32_e32 v83, v83, v133
	v_mul_f32_e32 v84, v84, v133
	v_mul_f32_e32 v85, v85, v133
	v_mul_f32_e32 v86, v86, v133
	v_mul_f32_e32 v87, v87, v133
	v_mul_f32_e32 v92, v92, v133
	v_mul_f32_e32 v93, v93, v133
	v_mul_f32_e32 v94, v94, v133
	v_mul_f32_e32 v95, v95, v133
	v_mul_f32_e32 v96, v96, v133
	v_mul_f32_e32 v97, v97, v133
	v_mul_f32_e32 v98, v98, v133
	v_mul_f32_e32 v99, v99, v133
	v_fma_f32 v80, v80, v32, v48
	v_fma_f32 v81, v81, v33, v49
	v_fma_f32 v82, v82, v34, v50
	v_fma_f32 v83, v83, v35, v51
	v_fma_f32 v84, v84, v36, v52
	v_fma_f32 v85, v85, v37, v53
	v_fma_f32 v86, v86, v38, v54
	v_fma_f32 v87, v87, v39, v55
	v_fma_f32 v92, v92, v40, v56
	v_fma_f32 v93, v93, v41, v57
	v_fma_f32 v94, v94, v42, v58
	v_fma_f32 v95, v95, v43, v59
	v_fma_f32 v96, v96, v44, v60
	v_fma_f32 v97, v97, v45, v61
	v_fma_f32 v98, v98, v46, v62
	v_fma_f32 v99, v99, v47, v63
	v_cvt_pk_bf16_f32 v100, v64, v80
	v_cvt_pk_bf16_f32 v102, v65, v81
	v_cvt_pk_bf16_f32 v104, v66, v82
	v_cvt_pk_bf16_f32 v106, v67, v83
	v_cvt_pk_bf16_f32 v108, v68, v84
	v_cvt_pk_bf16_f32 v110, v69, v85
	v_cvt_pk_bf16_f32 v112, v70, v86
	v_cvt_pk_bf16_f32 v114, v71, v87
	v_cvt_pk_bf16_f32 v116, v72, v92
	v_cvt_pk_bf16_f32 v118, v73, v93
	v_cvt_pk_bf16_f32 v120, v74, v94
	v_cvt_pk_bf16_f32 v122, v75, v95
	v_cvt_pk_bf16_f32 v124, v76, v96
	v_cvt_pk_bf16_f32 v126, v77, v97
	v_cvt_pk_bf16_f32 v128, v78, v98
	v_cvt_pk_bf16_f32 v130, v79, v99
	v_lshlrev_b32_e32 v64, 16, v16
	v_and_b32_e32 v65, 0xffff0000, v16
	v_lshlrev_b32_e32 v66, 16, v17
	v_and_b32_e32 v67, 0xffff0000, v17
	v_lshlrev_b32_e32 v68, 16, v18
	v_and_b32_e32 v69, 0xffff0000, v18
	v_lshlrev_b32_e32 v70, 16, v19
	v_and_b32_e32 v71, 0xffff0000, v19
	v_lshlrev_b32_e32 v72, 16, v20
	v_and_b32_e32 v73, 0xffff0000, v20
	v_lshlrev_b32_e32 v74, 16, v21
	v_and_b32_e32 v75, 0xffff0000, v21
	v_lshlrev_b32_e32 v76, 16, v22
	v_and_b32_e32 v77, 0xffff0000, v22
	v_lshlrev_b32_e32 v78, 16, v23
	v_and_b32_e32 v79, 0xffff0000, v23
	v_mul_f32_e32 v132, v64, v64
	v_mul_f32_e32 v133, v65, v65
	v_mul_f32_e32 v134, v66, v66
	v_mul_f32_e32 v135, v67, v67
	v_mul_f32_e32 v136, v68, v68
	v_mul_f32_e32 v137, v69, v69
	v_mul_f32_e32 v138, v70, v70
	v_mul_f32_e32 v139, v71, v71
	v_mul_f32_e32 v140, v72, v72
	v_mul_f32_e32 v141, v73, v73
	v_mul_f32_e32 v142, v74, v74
	v_mul_f32_e32 v143, v75, v75
	v_mul_f32_e32 v144, v76, v76
	v_mul_f32_e32 v145, v77, v77
	v_mul_f32_e32 v146, v78, v78
	v_mul_f32_e32 v147, v79, v79
	v_fma_f32 v132, v132, v191, v190
	v_fma_f32 v133, v133, v191, v190
	v_fma_f32 v134, v134, v191, v190
	v_fma_f32 v135, v135, v191, v190
	v_fma_f32 v136, v136, v191, v190
	v_fma_f32 v137, v137, v191, v190
	v_fma_f32 v138, v138, v191, v190
	v_fma_f32 v139, v139, v191, v190
	v_fma_f32 v140, v140, v191, v190
	v_fma_f32 v141, v141, v191, v190
	v_fma_f32 v142, v142, v191, v190
	v_fma_f32 v143, v143, v191, v190
	v_fma_f32 v144, v144, v191, v190
	v_fma_f32 v145, v145, v191, v190
	v_fma_f32 v146, v146, v191, v190
	v_fma_f32 v147, v147, v191, v190
	v_mul_f32_e32 v132, v132, v64
	v_mul_f32_e32 v133, v133, v65
	v_mul_f32_e32 v134, v134, v66
	v_mul_f32_e32 v135, v135, v67
	v_mul_f32_e32 v136, v136, v68
	v_mul_f32_e32 v137, v137, v69
	v_mul_f32_e32 v138, v138, v70
	v_mul_f32_e32 v139, v139, v71
	v_mul_f32_e32 v140, v140, v72
	v_mul_f32_e32 v141, v141, v73
	v_mul_f32_e32 v142, v142, v74
	v_mul_f32_e32 v143, v143, v75
	v_mul_f32_e32 v144, v144, v76
	v_mul_f32_e32 v145, v145, v77
	v_mul_f32_e32 v146, v146, v78
	v_mul_f32_e32 v147, v147, v79
	v_exp_f32_e32 v132, v132
	v_exp_f32_e32 v133, v133
	v_exp_f32_e32 v134, v134
	v_exp_f32_e32 v135, v135
	v_exp_f32_e32 v136, v136
	v_exp_f32_e32 v137, v137
	v_exp_f32_e32 v138, v138
	v_exp_f32_e32 v139, v139
	v_exp_f32_e32 v140, v140
	v_exp_f32_e32 v141, v141
	v_exp_f32_e32 v142, v142
	v_exp_f32_e32 v143, v143
	v_exp_f32_e32 v144, v144
	v_exp_f32_e32 v145, v145
	v_exp_f32_e32 v146, v146
	v_exp_f32_e32 v147, v147
	s_nop 0
	v_add_f32_e32 v132, 1.0, v132
	v_add_f32_e32 v133, 1.0, v133
	v_add_f32_e32 v134, 1.0, v134
	v_add_f32_e32 v135, 1.0, v135
	v_add_f32_e32 v136, 1.0, v136
	v_add_f32_e32 v137, 1.0, v137
	v_add_f32_e32 v138, 1.0, v138
	v_add_f32_e32 v139, 1.0, v139
	v_add_f32_e32 v140, 1.0, v140
	v_add_f32_e32 v141, 1.0, v141
	v_add_f32_e32 v142, 1.0, v142
	v_add_f32_e32 v143, 1.0, v143
	v_add_f32_e32 v144, 1.0, v144
	v_add_f32_e32 v145, 1.0, v145
	v_add_f32_e32 v146, 1.0, v146
	v_add_f32_e32 v147, 1.0, v147
	v_rcp_f32_e32 v132, v132
	v_rcp_f32_e32 v133, v133
	v_rcp_f32_e32 v134, v134
	v_rcp_f32_e32 v135, v135
	v_rcp_f32_e32 v136, v136
	v_rcp_f32_e32 v137, v137
	v_rcp_f32_e32 v138, v138
	v_rcp_f32_e32 v139, v139
	v_rcp_f32_e32 v140, v140
	v_rcp_f32_e32 v141, v141
	v_rcp_f32_e32 v142, v142
	v_rcp_f32_e32 v143, v143
	v_rcp_f32_e32 v144, v144
	v_rcp_f32_e32 v145, v145
	v_rcp_f32_e32 v146, v146
	v_rcp_f32_e32 v147, v147
	s_nop 0
	v_mul_f32_e32 v64, v64, v132
	v_mul_f32_e32 v65, v65, v133
	v_mul_f32_e32 v66, v66, v134
	v_mul_f32_e32 v67, v67, v135
	v_mul_f32_e32 v68, v68, v136
	v_mul_f32_e32 v69, v69, v137
	v_mul_f32_e32 v70, v70, v138
	v_mul_f32_e32 v71, v71, v139
	v_mul_f32_e32 v72, v72, v140
	v_mul_f32_e32 v73, v73, v141
	v_mul_f32_e32 v74, v74, v142
	v_mul_f32_e32 v75, v75, v143
	v_mul_f32_e32 v76, v76, v144
	v_mul_f32_e32 v77, v77, v145
	v_mul_f32_e32 v78, v78, v146
	v_mul_f32_e32 v79, v79, v147
	v_add_f32_e32 v132, v64, v65
	v_add_f32_e32 v132, v132, v66
; #define LAS __attribute__((address_space(3)))
; DI unsigned short f2bf(float f) { return (unsigned short)(pk2(f, 0.f) & 0xffffu); }
; DI float gelu_f(float x) { return x * __builtin_amdgcn_rcpf(1.f + __builtin_amdgcn_exp2f(x * (-2.302208198f + -0.102943240f * (x * x)))); }
; __global__ void __launch_bounds__(512, 2) fwd_megakernel(Args args) {
;     ...
;                     float v[64]; float sm = 0.f;
; #pragma unroll
;                     for (int k = 0; k < 8; ++k) { float t8[8]; unpack8(gvr[k], t8);
; #pragma unroll
;                         for (int i = 0; i < 8; ++i) { v[8 * k + i] = gelu_f(t8[i]); sm += v[8 * k + i]; } }
;                     sm += __shfl_xor(sm, 1); sm += __shfl_xor(sm, 2);
;                     const float mean = sm * (1.f / 256.f); float qv = 0.f;
; #pragma unroll
;                     for (int i = 0; i < 64; ++i) { const float d = v[i] - mean; qv += d * d; }
;                     qv += __shfl_xor(qv, 1); qv += __shfl_xor(qv, 2);
;                     const float rstd = rsqrtf(qv * (1.f / 256.f) + EPS);
;                     const float* lw = args.in[16] + layer * 256 + sub * 64; const float* lb = args.in[17] + layer * 256 + sub * 64;
;                     LAS bf16* dst = vnT + sub * (64 * 136) + l;
; #pragma unroll
;                     for (int i = 0; i < 64; ++i) dst[i * 136] = f2bf((v[i] - mean) * rstd * lw[i] + lb[i]);
	v_add_f32_e32 v132, v132, v67
	v_add_f32_e32 v132, v132, v68
	v_add_f32_e32 v132, v132, v69
	v_add_f32_e32 v132, v132, v70
	v_add_f32_e32 v132, v132, v71
	v_add_f32_e32 v132, v132, v72
	v_add_f32_e32 v132, v132, v73
	v_add_f32_e32 v132, v132, v74
	v_add_f32_e32 v132, v132, v75
	v_add_f32_e32 v132, v132, v76
	v_add_f32_e32 v132, v132, v77
	v_add_f32_e32 v132, v132, v78
	v_add_f32_e32 v132, v132, v79
	s_nop 1
	v_add_f32_dpp v132, v132, v132 quad_perm:[1,0,3,2] row_mask:0xf bank_mask:0xf
	s_nop 1
	v_add_f32_dpp v132, v132, v132 quad_perm:[2,3,0,1] row_mask:0xf bank_mask:0xf
	s_nop 1
	v_add_f32_dpp v132, v132, v132 row_half_mirror row_mask:0xf bank_mask:0xf
	s_nop 1
	v_add_f32_dpp v132, v132, v132 row_mirror row_mask:0xf bank_mask:0xf
	s_nop 1
	v_mul_f32_e32 v132, 0x3b800000, v132
	v_sub_f32_e32 v64, v64, v132
	v_sub_f32_e32 v65, v65, v132
	v_sub_f32_e32 v66, v66, v132
	v_sub_f32_e32 v67, v67, v132
	v_sub_f32_e32 v68, v68, v132
	v_sub_f32_e32 v69, v69, v132
	v_sub_f32_e32 v70, v70, v132
	v_sub_f32_e32 v71, v71, v132
	v_sub_f32_e32 v72, v72, v132
	v_sub_f32_e32 v73, v73, v132
	v_sub_f32_e32 v74, v74, v132
	v_sub_f32_e32 v75, v75, v132
	v_sub_f32_e32 v76, v76, v132
	v_sub_f32_e32 v77, v77, v132
	v_sub_f32_e32 v78, v78, v132
	v_sub_f32_e32 v79, v79, v132
	v_mul_f32_e32 v133, v64, v64
	v_fmac_f32_e32 v133, v65, v65
	v_fmac_f32_e32 v133, v66, v66
	v_fmac_f32_e32 v133, v67, v67
	v_fmac_f32_e32 v133, v68, v68
	v_fmac_f32_e32 v133, v69, v69
	v_fmac_f32_e32 v133, v70, v70
	v_fmac_f32_e32 v133, v71, v71
	v_fmac_f32_e32 v133, v72, v72
	v_fmac_f32_e32 v133, v73, v73
	v_fmac_f32_e32 v133, v74, v74
	v_fmac_f32_e32 v133, v75, v75
	v_fmac_f32_e32 v133, v76, v76
	v_fmac_f32_e32 v133, v77, v77
	v_fmac_f32_e32 v133, v78, v78
	v_fmac_f32_e32 v133, v79, v79
	s_nop 1
	v_add_f32_dpp v133, v133, v133 quad_perm:[1,0,3,2] row_mask:0xf bank_mask:0xf
	s_nop 1
	v_add_f32_dpp v133, v133, v133 quad_perm:[2,3,0,1] row_mask:0xf bank_mask:0xf
	s_nop 1
	v_add_f32_dpp v133, v133, v133 row_half_mirror row_mask:0xf bank_mask:0xf
	s_nop 1
	v_add_f32_dpp v133, v133, v133 row_mirror row_mask:0xf bank_mask:0xf
	s_nop 1
	v_mov_b32_e32 v134, 0x358637bd
	v_fmamk_f32 v133, v133, 0x3b800000, v134
	v_rsq_f32_e32 v133, v133
	s_nop 0
	v_mul_f32_e32 v64, v64, v133
	v_mul_f32_e32 v65, v65, v133
	v_mul_f32_e32 v66, v66, v133
	v_mul_f32_e32 v67, v67, v133
	v_mul_f32_e32 v68, v68, v133
	v_mul_f32_e32 v69, v69, v133
	v_mul_f32_e32 v70, v70, v133
	v_mul_f32_e32 v71, v71, v133
	v_mul_f32_e32 v72, v72, v133
	v_mul_f32_e32 v73, v73, v133
	v_mul_f32_e32 v74, v74, v133
	v_mul_f32_e32 v75, v75, v133
	v_mul_f32_e32 v76, v76, v133
	v_mul_f32_e32 v77, v77, v133
	v_mul_f32_e32 v78, v78, v133
	v_mul_f32_e32 v79, v79, v133
	v_fma_f32 v64, v64, v32, v48
	v_fma_f32 v65, v65, v33, v49
	v_fma_f32 v66, v66, v34, v50
	v_fma_f32 v67, v67, v35, v51
	v_fma_f32 v68, v68, v36, v52
	v_fma_f32 v69, v69, v37, v53
	v_fma_f32 v70, v70, v38, v54
	v_fma_f32 v71, v71, v39, v55
	v_fma_f32 v72, v72, v40, v56
	v_fma_f32 v73, v73, v41, v57
	v_fma_f32 v74, v74, v42, v58
	v_fma_f32 v75, v75, v43, v59
	v_fma_f32 v76, v76, v44, v60
	v_fma_f32 v77, v77, v45, v61
	v_fma_f32 v78, v78, v46, v62
	v_fma_f32 v79, v79, v47, v63
	v_lshlrev_b32_e32 v80, 16, v24
	v_and_b32_e32 v81, 0xffff0000, v24
	v_lshlrev_b32_e32 v82, 16, v25
	v_and_b32_e32 v83, 0xffff0000, v25
	v_lshlrev_b32_e32 v84, 16, v26
	v_and_b32_e32 v85, 0xffff0000, v26
	v_lshlrev_b32_e32 v86, 16, v27
	v_and_b32_e32 v87, 0xffff0000, v27
	v_lshlrev_b32_e32 v92, 16, v28
	v_and_b32_e32 v93, 0xffff0000, v28
	v_lshlrev_b32_e32 v94, 16, v29
	v_and_b32_e32 v95, 0xffff0000, v29
	v_lshlrev_b32_e32 v96, 16, v30
	v_and_b32_e32 v97, 0xffff0000, v30
	v_lshlrev_b32_e32 v98, 16, v31
	v_and_b32_e32 v99, 0xffff0000, v31
	v_mul_f32_e32 v132, v80, v80
	v_mul_f32_e32 v133, v81, v81
	v_mul_f32_e32 v134, v82, v82
	v_mul_f32_e32 v135, v83, v83
	v_mul_f32_e32 v136, v84, v84
	v_mul_f32_e32 v137, v85, v85
	v_mul_f32_e32 v138, v86, v86
	v_mul_f32_e32 v139, v87, v87
	v_mul_f32_e32 v140, v92, v92
	v_mul_f32_e32 v141, v93, v93
	v_mul_f32_e32 v142, v94, v94
	v_mul_f32_e32 v143, v95, v95
	v_mul_f32_e32 v144, v96, v96
	v_mul_f32_e32 v145, v97, v97
	v_mul_f32_e32 v146, v98, v98
	v_mul_f32_e32 v147, v99, v99
	v_fma_f32 v132, v132, v191, v190
	v_fma_f32 v133, v133, v191, v190
	v_fma_f32 v134, v134, v191, v190
	v_fma_f32 v135, v135, v191, v190
	v_fma_f32 v136, v136, v191, v190
	v_fma_f32 v137, v137, v191, v190
	v_fma_f32 v138, v138, v191, v190
	v_fma_f32 v139, v139, v191, v190
	v_fma_f32 v140, v140, v191, v190
	v_fma_f32 v141, v141, v191, v190
	v_fma_f32 v142, v142, v191, v190
	v_fma_f32 v143, v143, v191, v190
	v_fma_f32 v144, v144, v191, v190
	v_fma_f32 v145, v145, v191, v190
	v_fma_f32 v146, v146, v191, v190
	v_fma_f32 v147, v147, v191, v190
	v_mul_f32_e32 v132, v132, v80
	v_mul_f32_e32 v133, v133, v81
	v_mul_f32_e32 v134, v134, v82
	v_mul_f32_e32 v135, v135, v83
	v_mul_f32_e32 v136, v136, v84
	v_mul_f32_e32 v137, v137, v85
	v_mul_f32_e32 v138, v138, v86
	v_mul_f32_e32 v139, v139, v87
	v_mul_f32_e32 v140, v140, v92
	v_mul_f32_e32 v141, v141, v93
	v_mul_f32_e32 v142, v142, v94
	v_mul_f32_e32 v143, v143, v95
	v_mul_f32_e32 v144, v144, v96
	v_mul_f32_e32 v145, v145, v97
	v_mul_f32_e32 v146, v146, v98
	v_mul_f32_e32 v147, v147, v99
	v_exp_f32_e32 v132, v132
	v_exp_f32_e32 v133, v133
	v_exp_f32_e32 v134, v134
	v_exp_f32_e32 v135, v135
	v_exp_f32_e32 v136, v136
	v_exp_f32_e32 v137, v137
	v_exp_f32_e32 v138, v138
	v_exp_f32_e32 v139, v139
	v_exp_f32_e32 v140, v140
	v_exp_f32_e32 v141, v141
	v_exp_f32_e32 v142, v142
	v_exp_f32_e32 v143, v143
	v_exp_f32_e32 v144, v144
	v_exp_f32_e32 v145, v145
	v_exp_f32_e32 v146, v146
; #define LAS __attribute__((address_space(3)))
; DI unsigned short f2bf(float f) { return (unsigned short)(pk2(f, 0.f) & 0xffffu); }
; DI float gelu_f(float x) { return x * __builtin_amdgcn_rcpf(1.f + __builtin_amdgcn_exp2f(x * (-2.302208198f + -0.102943240f * (x * x)))); }
; __global__ void __launch_bounds__(512, 2) fwd_megakernel(Args args) {
;     ...
;                     float v[64]; float sm = 0.f;
; #pragma unroll
;                     for (int k = 0; k < 8; ++k) { float t8[8]; unpack8(gvr[k], t8);
; #pragma unroll
;                         for (int i = 0; i < 8; ++i) { v[8 * k + i] = gelu_f(t8[i]); sm += v[8 * k + i]; } }
;                     sm += __shfl_xor(sm, 1); sm += __shfl_xor(sm, 2);
;                     const float mean = sm * (1.f / 256.f); float qv = 0.f;
; #pragma unroll
;                     for (int i = 0; i < 64; ++i) { const float d = v[i] - mean; qv += d * d; }
;                     qv += __shfl_xor(qv, 1); qv += __shfl_xor(qv, 2);
;                     const float rstd = rsqrtf(qv * (1.f / 256.f) + EPS);
;                     const float* lw = args.in[16] + layer * 256 + sub * 64; const float* lb = args.in[17] + layer * 256 + sub * 64;
;                     LAS bf16* dst = vnT + sub * (64 * 136) + l;
; #pragma unroll
;                     for (int i = 0; i < 64; ++i) dst[i * 136] = f2bf((v[i] - mean) * rstd * lw[i] + lb[i]);
	v_exp_f32_e32 v147, v147
	s_nop 0
	v_add_f32_e32 v132, 1.0, v132
	v_add_f32_e32 v133, 1.0, v133
	v_add_f32_e32 v134, 1.0, v134
	v_add_f32_e32 v135, 1.0, v135
	v_add_f32_e32 v136, 1.0, v136
	v_add_f32_e32 v137, 1.0, v137
	v_add_f32_e32 v138, 1.0, v138
	v_add_f32_e32 v139, 1.0, v139
	v_add_f32_e32 v140, 1.0, v140
	v_add_f32_e32 v141, 1.0, v141
	v_add_f32_e32 v142, 1.0, v142
	v_add_f32_e32 v143, 1.0, v143
	v_add_f32_e32 v144, 1.0, v144
	v_add_f32_e32 v145, 1.0, v145
	v_add_f32_e32 v146, 1.0, v146
	v_add_f32_e32 v147, 1.0, v147
	v_rcp_f32_e32 v132, v132
	v_rcp_f32_e32 v133, v133
	v_rcp_f32_e32 v134, v134
	v_rcp_f32_e32 v135, v135
	v_rcp_f32_e32 v136, v136
	v_rcp_f32_e32 v137, v137
	v_rcp_f32_e32 v138, v138
	v_rcp_f32_e32 v139, v139
	v_rcp_f32_e32 v140, v140
	v_rcp_f32_e32 v141, v141
	v_rcp_f32_e32 v142, v142
	v_rcp_f32_e32 v143, v143
	v_rcp_f32_e32 v144, v144
	v_rcp_f32_e32 v145, v145
	v_rcp_f32_e32 v146, v146
	v_rcp_f32_e32 v147, v147
	s_nop 0
	v_mul_f32_e32 v80, v80, v132
	v_mul_f32_e32 v81, v81, v133
	v_mul_f32_e32 v82, v82, v134
	v_mul_f32_e32 v83, v83, v135
	v_mul_f32_e32 v84, v84, v136
	v_mul_f32_e32 v85, v85, v137
	v_mul_f32_e32 v86, v86, v138
	v_mul_f32_e32 v87, v87, v139
	v_mul_f32_e32 v92, v92, v140
	v_mul_f32_e32 v93, v93, v141
	v_mul_f32_e32 v94, v94, v142
	v_mul_f32_e32 v95, v95, v143
	v_mul_f32_e32 v96, v96, v144
	v_mul_f32_e32 v97, v97, v145
	v_mul_f32_e32 v98, v98, v146
	v_mul_f32_e32 v99, v99, v147
	v_add_f32_e32 v132, v80, v81
	v_add_f32_e32 v132, v132, v82
	v_add_f32_e32 v132, v132, v83
	v_add_f32_e32 v132, v132, v84
	v_add_f32_e32 v132, v132, v85
	v_add_f32_e32 v132, v132, v86
	v_add_f32_e32 v132, v132, v87
	v_add_f32_e32 v132, v132, v92
	v_add_f32_e32 v132, v132, v93
	v_add_f32_e32 v132, v132, v94
	v_add_f32_e32 v132, v132, v95
	v_add_f32_e32 v132, v132, v96
	v_add_f32_e32 v132, v132, v97
	v_add_f32_e32 v132, v132, v98
	v_add_f32_e32 v132, v132, v99
	s_nop 1
	v_add_f32_dpp v132, v132, v132 quad_perm:[1,0,3,2] row_mask:0xf bank_mask:0xf
	s_nop 1
	v_add_f32_dpp v132, v132, v132 quad_perm:[2,3,0,1] row_mask:0xf bank_mask:0xf
	s_nop 1
	v_add_f32_dpp v132, v132, v132 row_half_mirror row_mask:0xf bank_mask:0xf
	s_nop 1
	v_add_f32_dpp v132, v132, v132 row_mirror row_mask:0xf bank_mask:0xf
	s_nop 1
	v_mul_f32_e32 v132, 0x3b800000, v132
	v_sub_f32_e32 v80, v80, v132
	v_sub_f32_e32 v81, v81, v132
	v_sub_f32_e32 v82, v82, v132
	v_sub_f32_e32 v83, v83, v132
	v_sub_f32_e32 v84, v84, v132
	v_sub_f32_e32 v85, v85, v132
	v_sub_f32_e32 v86, v86, v132
	v_sub_f32_e32 v87, v87, v132
	v_sub_f32_e32 v92, v92, v132
	v_sub_f32_e32 v93, v93, v132
	v_sub_f32_e32 v94, v94, v132
	v_sub_f32_e32 v95, v95, v132
	v_sub_f32_e32 v96, v96, v132
	v_sub_f32_e32 v97, v97, v132
	v_sub_f32_e32 v98, v98, v132
	v_sub_f32_e32 v99, v99, v132
	v_mul_f32_e32 v133, v80, v80
	v_fmac_f32_e32 v133, v81, v81
	v_fmac_f32_e32 v133, v82, v82
	v_fmac_f32_e32 v133, v83, v83
	v_fmac_f32_e32 v133, v84, v84
	v_fmac_f32_e32 v133, v85, v85
	v_fmac_f32_e32 v133, v86, v86
	v_fmac_f32_e32 v133, v87, v87
	v_fmac_f32_e32 v133, v92, v92
	v_fmac_f32_e32 v133, v93, v93
	v_fmac_f32_e32 v133, v94, v94
	v_fmac_f32_e32 v133, v95, v95
	v_fmac_f32_e32 v133, v96, v96
	v_fmac_f32_e32 v133, v97, v97
	v_fmac_f32_e32 v133, v98, v98
	v_fmac_f32_e32 v133, v99, v99
	s_nop 1
	v_add_f32_dpp v133, v133, v133 quad_perm:[1,0,3,2] row_mask:0xf bank_mask:0xf
	s_nop 1
	v_add_f32_dpp v133, v133, v133 quad_perm:[2,3,0,1] row_mask:0xf bank_mask:0xf
	s_nop 1
	v_add_f32_dpp v133, v133, v133 row_half_mirror row_mask:0xf bank_mask:0xf
	s_nop 1
	v_add_f32_dpp v133, v133, v133 row_mirror row_mask:0xf bank_mask:0xf
	s_nop 1
	v_mov_b32_e32 v134, 0x358637bd
	v_fmamk_f32 v133, v133, 0x3b800000, v134
	v_rsq_f32_e32 v133, v133
	s_nop 0
	v_mul_f32_e32 v80, v80, v133
	v_mul_f32_e32 v81, v81, v133
	v_mul_f32_e32 v82, v82, v133
	v_mul_f32_e32 v83, v83, v133
	v_mul_f32_e32 v84, v84, v133
	v_mul_f32_e32 v85, v85, v133
	v_mul_f32_e32 v86, v86, v133
	v_mul_f32_e32 v87, v87, v133
	v_mul_f32_e32 v92, v92, v133
	v_mul_f32_e32 v93, v93, v133
	v_mul_f32_e32 v94, v94, v133
	v_mul_f32_e32 v95, v95, v133
	v_mul_f32_e32 v96, v96, v133
	v_mul_f32_e32 v97, v97, v133
	v_mul_f32_e32 v98, v98, v133
	v_mul_f32_e32 v99, v99, v133
	v_fma_f32 v80, v80, v32, v48
	v_fma_f32 v81, v81, v33, v49
	v_fma_f32 v82, v82, v34, v50
	v_fma_f32 v83, v83, v35, v51
	v_fma_f32 v84, v84, v36, v52
	v_fma_f32 v85, v85, v37, v53
	v_fma_f32 v86, v86, v38, v54
	v_fma_f32 v87, v87, v39, v55
	v_fma_f32 v92, v92, v40, v56
	v_fma_f32 v93, v93, v41, v57
	v_fma_f32 v94, v94, v42, v58
	v_fma_f32 v95, v95, v43, v59
	v_fma_f32 v96, v96, v44, v60
	v_fma_f32 v97, v97, v45, v61
	v_fma_f32 v98, v98, v46, v62
	v_fma_f32 v99, v99, v47, v63
	v_cvt_pk_bf16_f32 v101, v64, v80
	v_cvt_pk_bf16_f32 v103, v65, v81
	v_cvt_pk_bf16_f32 v105, v66, v82
	v_cvt_pk_bf16_f32 v107, v67, v83
	v_cvt_pk_bf16_f32 v109, v68, v84
	v_cvt_pk_bf16_f32 v111, v69, v85
	v_cvt_pk_bf16_f32 v113, v70, v86
	v_cvt_pk_bf16_f32 v115, v71, v87
	v_cvt_pk_bf16_f32 v117, v72, v92
	v_cvt_pk_bf16_f32 v119, v73, v93
	v_cvt_pk_bf16_f32 v121, v74, v94
	v_cvt_pk_bf16_f32 v123, v75, v95
	v_cvt_pk_bf16_f32 v125, v76, v96
	v_cvt_pk_bf16_f32 v127, v77, v97
	v_cvt_pk_bf16_f32 v129, v78, v98
	v_cvt_pk_bf16_f32 v131, v79, v99
	ds_write_b64 v189, v[100:101] offset:0
	ds_write_b64 v189, v[102:103] offset:272
	ds_write_b64 v189, v[104:105] offset:544
	ds_write_b64 v189, v[106:107] offset:816
	ds_write_b64 v189, v[108:109] offset:1088
	ds_write_b64 v189, v[110:111] offset:1360
	ds_write_b64 v189, v[112:113] offset:1632
	ds_write_b64 v189, v[114:115] offset:1904
	ds_write_b64 v189, v[116:117] offset:2176
	ds_write_b64 v189, v[118:119] offset:2448
	ds_write_b64 v189, v[120:121] offset:2720
	ds_write_b64 v189, v[122:123] offset:2992
	ds_write_b64 v189, v[124:125] offset:3264
	ds_write_b64 v189, v[126:127] offset:3536
	ds_write_b64 v189, v[128:129] offset:3808
	ds_write_b64 v189, v[130:131] offset:4080
	s_waitcnt lgkmcnt(0)
; DI f32x4 mfma16(bf16x8 a, bf16x8 b, f32x4 c) { return __builtin_amdgcn_mfma_f32_16x16x32_bf16(a, b, c, 0, 0, 0); }
; __global__ void __launch_bounds__(512, 2) fwd_megakernel(Args args) {
;     ...
;                 for (int gi = 0; gi < 4; ++gi)
; #pragma unroll
;                     for (int ks = 0; ks < 4; ++ks) wa[gi][ks] = *(const bf16x8*)(sguW + (size_t)(layer * 4 + gi) * 16384 + (16 * wave + r16) * 128 + ks * 32 + q4 * 8);
;                 __syncthreads();
;                 {
;                     f32x4 og[4][4]; float ss[4] = {0.f, 0.f, 0.f, 0.f};
; #pragma unroll
;                     for (int gi = 0; gi < 4; ++gi) {
;                         f32x4 acc[4];
; #pragma unroll
;                         for (int dt = 0; dt < 4; ++dt) acc[dt] = (f32x4){0.f, 0.f, 0.f, 0.f};
; #pragma unroll
;                         for (int ks = 0; ks < 4; ++ks) {
;                             if (2 * ks <= wave) {
; #pragma unroll
;                                 for (int dt = 0; dt < 4; ++dt) acc[dt] = mfma16(wa[gi][ks], lds_frag(vnT + gi * (64 * 136), 16 * dt + r16, 136, ks * 32 + q4 * 8), acc[dt]);
	v_lshlrev_b32_e32 v188, 8, v187
	v_lshl_add_u32 v188, v186, 4, v188
	global_load_dwordx4 v[64:67], v188, s[12:13] offset:0
	global_load_dwordx4 v[68:71], v188, s[12:13] offset:64
	global_load_dwordx4 v[72:75], v188, s[12:13] offset:128
	global_load_dwordx4 v[76:79], v188, s[12:13] offset:192
	v_add_u32_e32 v188, 0x8000, v188
	global_load_dwordx4 v[80:83], v188, s[12:13] offset:0
	global_load_dwordx4 v[84:87], v188, s[12:13] offset:64
	global_load_dwordx4 v[92:95], v188, s[12:13] offset:128
	global_load_dwordx4 v[96:99], v188, s[12:13] offset:192
	v_add_u32_e32 v188, 0x8000, v188
	global_load_dwordx4 v[100:103], v188, s[12:13] offset:0
	global_load_dwordx4 v[104:107], v188, s[12:13] offset:64
	global_load_dwordx4 v[108:111], v188, s[12:13] offset:128
	global_load_dwordx4 v[112:115], v188, s[12:13] offset:192
	v_add_u32_e32 v188, 0x8000, v188
	global_load_dwordx4 v[116:119], v188, s[12:13] offset:0
	global_load_dwordx4 v[120:123], v188, s[12:13] offset:64
	global_load_dwordx4 v[124:127], v188, s[12:13] offset:128
	global_load_dwordx4 v[128:131], v188, s[12:13] offset:192
	v_mul_u32_u24_e32 v197, 0x110, v185
	v_lshl_add_u32 v197, v186, 4, v197
	s_waitcnt lgkmcnt(0)
	s_barrier
	s_waitcnt vmcnt(0)
	ds_read_b128 v[132:135], v197 offset:0
	ds_read_b128 v[136:139], v197 offset:4352
	ds_read_b128 v[140:143], v197 offset:8704
	ds_read_b128 v[144:147], v197 offset:13056
	s_waitcnt lgkmcnt(0)
	v_mfma_f32_16x16x32_bf16 v[0:3], v[132:135], v[64:67], 0
	v_mfma_f32_16x16x32_bf16 v[4:7], v[136:139], v[64:67], 0
	v_mfma_f32_16x16x32_bf16 v[8:11], v[140:143], v[64:67], 0
	v_mfma_f32_16x16x32_bf16 v[12:15], v[144:147], v[64:67], 0
	s_cmp_lt_u32 s2, 2
	s_cbranch_scc1 .Lm1c_g0_done
	ds_read_b128 v[132:135], v197 offset:64
	ds_read_b128 v[136:139], v197 offset:4416
	ds_read_b128 v[140:143], v197 offset:8768
	ds_read_b128 v[144:147], v197 offset:13120
	s_waitcnt lgkmcnt(0)
	v_mfma_f32_16x16x32_bf16 v[0:3], v[132:135], v[68:71], v[0:3]
	v_mfma_f32_16x16x32_bf16 v[4:7], v[136:139], v[68:71], v[4:7]
	v_mfma_f32_16x16x32_bf16 v[8:11], v[140:143], v[68:71], v[8:11]
	v_mfma_f32_16x16x32_bf16 v[12:15], v[144:147], v[68:71], v[12:15]
	s_cmp_lt_u32 s2, 4
	s_cbranch_scc1 .Lm1c_g0_done
	ds_read_b128 v[132:135], v197 offset:128
	ds_read_b128 v[136:139], v197 offset:4480
	ds_read_b128 v[140:143], v197 offset:8832
	ds_read_b128 v[144:147], v197 offset:13184
	s_waitcnt lgkmcnt(0)
	v_mfma_f32_16x16x32_bf16 v[0:3], v[132:135], v[72:75], v[0:3]
	v_mfma_f32_16x16x32_bf16 v[4:7], v[136:139], v[72:75], v[4:7]
	v_mfma_f32_16x16x32_bf16 v[8:11], v[140:143], v[72:75], v[8:11]
	v_mfma_f32_16x16x32_bf16 v[12:15], v[144:147], v[72:75], v[12:15]
	s_cmp_lt_u32 s2, 6
	s_cbranch_scc1 .Lm1c_g0_done
	ds_read_b128 v[132:135], v197 offset:192
	ds_read_b128 v[136:139], v197 offset:4544
	ds_read_b128 v[140:143], v197 offset:8896
	ds_read_b128 v[144:147], v197 offset:13248
	s_waitcnt lgkmcnt(0)
	v_mfma_f32_16x16x32_bf16 v[0:3], v[132:135], v[76:79], v[0:3]
	v_mfma_f32_16x16x32_bf16 v[4:7], v[136:139], v[76:79], v[4:7]
	v_mfma_f32_16x16x32_bf16 v[8:11], v[140:143], v[76:79], v[8:11]
	v_mfma_f32_16x16x32_bf16 v[12:15], v[144:147], v[76:79], v[12:15]

; DI u32x4 pack8(const float (&v)[8]) { u32x4 r; r.x = pk2(v[0], v[1]); r.y = pk2(v[2], v[3]); r.z = pk2(v[4], v[5]); r.w = pk2(v[6], v[7]); return r; }
; #define PHASE_IDS() const int tid = opaque_tid(), lane = tid & 63, r16 = lane & 15, q4 = lane >> 4; (void)r16; (void)q4; (void)tid
; __global__ void __launch_bounds__(512, 2) fwd_megakernel(Args args) {
;     ...
;             for (int m0 = gw; m0 < MTOK; m0 += 4 * NGW) {
;                 PHASE_IDS();
;                 f32x4 sv[4][3]; u32x4 yv[4][2];
;                 const int colA = lane * 8, colB = 512 + lane * 8;
; #pragma unroll
;                 for (int r = 0; r < 4; ++r) { const int m = min(m0 + r * NGW, MTOK - 1);
;                     sv[r][0] = *(const f32x4*)(mss_g + (size_t)m * 4); sv[r][1] = *(const f32x4*)(mss_g + ((size_t)MTOK + m) * 4); sv[r][2] = (f32x4){mss_a[m], mss_a[(size_t)MTOK + m], mss_a[(size_t)2 * MTOK + m], mss_a[(size_t)3 * MTOK + m]};
;                     yv[r][0] = *(const u32x4*)(Yg + (size_t)m * DM + colA); yv[r][1] = *(const u32x4*)(Yg + (size_t)m * DM + 512 + (lane & 31) * 8); }
;                 float nwA[8], nwB[8];
;                 { const float* p = args.in[12] + layer * 512 + colA;
; #pragma unroll
;                   for (int i = 0; i < 8; ++i) nwA[i] = p[i];
;                   const float* q = args.in[15] + layer * 256 + (lane & 31) * 8;
; #pragma unroll
;                   for (int i = 0; i < 8; ++i) nwB[i] = q[i]; }
; #pragma unroll
;                 for (int r = 0; r < 4; ++r) { const int m = m0 + r * NGW; if (m < MTOK) {
;                     const f32x4 s0 = sv[r][0], s1 = sv[r][1], s2 = sv[r][2];
;                     const float r_ssd = rsqrtf((((s0.x + s0.y) + (s0.z + s0.w)) + ((s1.x + s1.y) + (s1.z + s1.w))) * (1.f / 512.f) + EPS);
;                     const float r_att = rsqrtf(((s2.x + s2.y) + (s2.z + s2.w)) * (1.f / 256.f) + EPS);
;                     float v[8]; unpack8(yv[r][0], v);
; #pragma unroll
;                     for (int i = 0; i < 8; ++i) v[i] = v[i] * r_ssd * nwA[i];
;                     *(u32x4*)(ycat + (size_t)m * DM + colA) = pack8(v);
;                     if (lane < 32) { unpack8(yv[r][1], v);
; #pragma unroll
;                         for (int i = 0; i < 8; ++i) v[i] = v[i] * r_att * nwB[i];
;                         *(u32x4*)(ycat + (size_t)m * DM + colB) = pack8(v); } } }
.Lm4f:
	s_waitcnt vmcnt(0) lgkmcnt(0)
	s_barrier
	v_readlane_b32 s2, v252, 0
	v_readlane_b32 s3, v251, 0
	s_and_b32 s29, s3, 7
	s_lshl_b32 s29, s29, 5
	s_lshr_b32 s3, s3, 3
	s_add_i32 s3, s3, s29
	s_lshl_b32 s3, s3, 7
	s_lshl_b32 s29, s2, 4
	s_add_i32 s3, s3, s29
	s_lshl_b32 s29, s3, 11
	s_add_u32 s4, s80, 0xa000000
	s_addc_u32 s5, s81, 0
	s_add_u32 s4, s4, s29
	s_addc_u32 s5, s5, 0
	s_add_u32 s6, s80, 0xe000000
	s_addc_u32 s7, s81, 0
	s_add_u32 s6, s6, s29
	s_addc_u32 s7, s7, 0
	s_lshl_b32 s29, s3, 4
	s_add_u32 s8, s80, 0x300000
	s_addc_u32 s9, s81, 0
	s_add_u32 s8, s8, s29
	s_addc_u32 s9, s9, 0
	s_lshl_b32 s29, s3, 2
	s_add_u32 s12, s80, 0x400000
	s_addc_u32 s13, s81, 0
	s_add_u32 s12, s12, s29
	s_addc_u32 s13, s13, 0
	v_readlane_b32 s29, v253, 58
	v_readlane_b32 s30, v251, 33
	v_readlane_b32 s31, v251, 34
	s_lshl_b32 s10, s29, 8
	s_add_u32 s30, s30, s10
	s_addc_u32 s31, s31, 0
	v_readlane_b32 s34, v251, 39
	v_readlane_b32 s35, v251, 40
	s_lshl_b32 s10, s29, 7
	s_add_u32 s34, s34, s10
	s_addc_u32 s35, s35, 0
	v_and_b32_e32 v116, 63, v195
	v_and_b32_e32 v161, 15, v116
	v_bfe_u32 v162, v116, 4, 2
	v_and_b32_e32 v163, 1, v162
	v_lshlrev_b32_e32 v163, 19, v163
	v_lshl_add_u32 v163, v161, 4, v163
	global_load_dwordx4 v[134:137], v163, s[8:9]
	v_lshlrev_b32_e32 v163, 17, v162
	v_lshl_add_u32 v163, v161, 2, v163
	global_load_dword v138, v163, s[12:13]
	v_lshlrev_b32_e32 v163, 5, v116
	global_load_dwordx4 v[118:121], v163, s[30:31]
	global_load_dwordx4 v[122:125], v163, s[30:31] offset:16
	v_and_b32_e32 v164, 31, v116
	v_lshlrev_b32_e32 v164, 5, v164
	global_load_dwordx4 v[126:129], v164, s[34:35]
	global_load_dwordx4 v[130:133], v164, s[34:35] offset:16
	v_xor_b32_e32 v165, 16, v116
	v_lshlrev_b32_e32 v165, 2, v165
	v_xor_b32_e32 v166, 32, v116
	v_lshlrev_b32_e32 v166, 2, v166
	v_lshlrev_b32_e32 v117, 4, v116
	s_waitcnt vmcnt(0)
	v_add_f32_e32 v134, v134, v135
	v_add_f32_e32 v136, v136, v137
	v_add_f32_e32 v134, v134, v136
	ds_bpermute_b32 v135, v165, v134
	ds_bpermute_b32 v139, v165, v138
	s_waitcnt lgkmcnt(0)
	v_add_f32_e32 v134, v134, v135
	v_add_f32_e32 v138, v138, v139
	ds_bpermute_b32 v139, v166, v138
	v_mov_b32_e32 v167, 0x358637bd
	v_fmamk_f32 v154, v134, 0x3b000000, v167
	v_rsq_f32_e32 v154, v154
	s_waitcnt lgkmcnt(0)
	v_add_f32_e32 v138, v138, v139
	v_fmamk_f32 v160, v138, 0x3b800000, v167
	v_rsq_f32_e32 v160, v160
	s_nop 0
	v_readlane_b32 s60, v154, 0
	v_readlane_b32 s61, v154, 1
	v_readlane_b32 s62, v154, 2
	v_readlane_b32 s63, v154, 3
	v_readlane_b32 s64, v154, 4
	v_readlane_b32 s65, v154, 5
	v_readlane_b32 s66, v154, 6
	v_readlane_b32 s67, v154, 7
	v_readlane_b32 s68, v154, 8
	v_readlane_b32 s69, v154, 9
	v_readlane_b32 s70, v154, 10
	v_readlane_b32 s71, v154, 11
	v_readlane_b32 s72, v154, 12
	v_readlane_b32 s73, v154, 13
	v_readlane_b32 s74, v154, 14
	v_readlane_b32 s75, v154, 15
	s_waitcnt vmcnt(0)
	v_add_u32_e32 v169, 0, v117
	global_load_dwordx4 v[170:173], v169, s[4:5]
	v_add_u32_e32 v169, 2048, v117
	global_load_dwordx4 v[174:177], v169, s[4:5]
	v_add_u32_e32 v169, 4096, v117
	global_load_dwordx4 v[178:181], v169, s[4:5]
	v_add_u32_e32 v169, 6144, v117
	global_load_dwordx4 v[182:185], v169, s[4:5]
	s_waitcnt vmcnt(0)
	v_add_u32_e32 v169, 0, v117
	v_lshlrev_b32_e32 v142, 16, v170
	v_and_b32_e32 v143, 0xffff0000, v170
	v_lshlrev_b32_e32 v144, 16, v171
	v_and_b32_e32 v145, 0xffff0000, v171
	v_lshlrev_b32_e32 v146, 16, v172
	v_and_b32_e32 v147, 0xffff0000, v172
	v_lshlrev_b32_e32 v148, 16, v173
	v_and_b32_e32 v149, 0xffff0000, v173
	v_mul_f32_e32 v142, s60, v142
	v_mul_f32_e32 v143, s60, v143
	v_mul_f32_e32 v144, s60, v144
	v_mul_f32_e32 v145, s60, v145
	v_mul_f32_e32 v146, s60, v146
	v_mul_f32_e32 v147, s60, v147
	v_mul_f32_e32 v148, s60, v148
	v_mul_f32_e32 v149, s60, v149
	v_mul_f32_e32 v142, v142, v118
	v_mul_f32_e32 v143, v143, v119
	v_mul_f32_e32 v144, v144, v120
	v_mul_f32_e32 v145, v145, v121
	v_mul_f32_e32 v146, v146, v122
	v_mul_f32_e32 v147, v147, v123
	v_mul_f32_e32 v148, v148, v124
	v_mul_f32_e32 v149, v149, v125
	v_cvt_pk_bf16_f32 v150, v142, v143
	v_cvt_pk_bf16_f32 v151, v144, v145
	v_cvt_pk_bf16_f32 v152, v146, v147
	v_cvt_pk_bf16_f32 v153, v148, v149
	global_store_dwordx4 v169, v[150:153], s[6:7] offset:0
	s_nop 1
	v_add_u32_e32 v169, 2048, v117
	v_lshlrev_b32_e32 v142, 16, v174
	v_and_b32_e32 v143, 0xffff0000, v174
	v_lshlrev_b32_e32 v144, 16, v175
	v_and_b32_e32 v145, 0xffff0000, v175
	v_lshlrev_b32_e32 v146, 16, v176
	v_and_b32_e32 v147, 0xffff0000, v176
	v_lshlrev_b32_e32 v148, 16, v177
	v_and_b32_e32 v149, 0xffff0000, v177
	v_mul_f32_e32 v142, s61, v142
	v_mul_f32_e32 v143, s61, v143
	v_mul_f32_e32 v144, s61, v144
	v_mul_f32_e32 v145, s61, v145
	v_mul_f32_e32 v146, s61, v146
	v_mul_f32_e32 v147, s61, v147
	v_mul_f32_e32 v148, s61, v148
	v_mul_f32_e32 v149, s61, v149
	v_mul_f32_e32 v142, v142, v118
	v_mul_f32_e32 v143, v143, v119
	v_mul_f32_e32 v144, v144, v120
	v_mul_f32_e32 v145, v145, v121
	v_mul_f32_e32 v146, v146, v122
	v_mul_f32_e32 v147, v147, v123
	v_mul_f32_e32 v148, v148, v124
	v_mul_f32_e32 v149, v149, v125
	v_cvt_pk_bf16_f32 v150, v142, v143
	v_cvt_pk_bf16_f32 v151, v144, v145
	v_cvt_pk_bf16_f32 v152, v146, v147
	v_cvt_pk_bf16_f32 v153, v148, v149
	global_store_dwordx4 v169, v[150:153], s[6:7] offset:0
	s_nop 1
	v_add_u32_e32 v169, 4096, v117
	v_lshlrev_b32_e32 v142, 16, v178
	v_and_b32_e32 v143, 0xffff0000, v178
	v_lshlrev_b32_e32 v144, 16, v179
	v_and_b32_e32 v145, 0xffff0000, v179
	v_lshlrev_b32_e32 v146, 16, v180
	v_and_b32_e32 v147, 0xffff0000, v180
	v_lshlrev_b32_e32 v148, 16, v181
	v_and_b32_e32 v149, 0xffff0000, v181
	v_mul_f32_e32 v142, s62, v142
	v_mul_f32_e32 v143, s62, v143
; DI u32x4 pack8(const float (&v)[8]) { u32x4 r; r.x = pk2(v[0], v[1]); r.y = pk2(v[2], v[3]); r.z = pk2(v[4], v[5]); r.w = pk2(v[6], v[7]); return r; }
; #define PHASE_IDS() const int tid = opaque_tid(), lane = tid & 63, r16 = lane & 15, q4 = lane >> 4; (void)r16; (void)q4; (void)tid
; __global__ void __launch_bounds__(512, 2) fwd_megakernel(Args args) {
;     ...
;             for (int m0 = gw; m0 < MTOK; m0 += 4 * NGW) {
;                 PHASE_IDS();
;                 f32x4 sv[4][3]; u32x4 yv[4][2];
;                 const int colA = lane * 8, colB = 512 + lane * 8;
; #pragma unroll
;                 for (int r = 0; r < 4; ++r) { const int m = min(m0 + r * NGW, MTOK - 1);
;                     sv[r][0] = *(const f32x4*)(mss_g + (size_t)m * 4); sv[r][1] = *(const f32x4*)(mss_g + ((size_t)MTOK + m) * 4); sv[r][2] = (f32x4){mss_a[m], mss_a[(size_t)MTOK + m], mss_a[(size_t)2 * MTOK + m], mss_a[(size_t)3 * MTOK + m]};
;                     yv[r][0] = *(const u32x4*)(Yg + (size_t)m * DM + colA); yv[r][1] = *(const u32x4*)(Yg + (size_t)m * DM + 512 + (lane & 31) * 8); }
;                 float nwA[8], nwB[8];
;                 { const float* p = args.in[12] + layer * 512 + colA;
; #pragma unroll
;                   for (int i = 0; i < 8; ++i) nwA[i] = p[i];
;                   const float* q = args.in[15] + layer * 256 + (lane & 31) * 8;
; #pragma unroll
;                   for (int i = 0; i < 8; ++i) nwB[i] = q[i]; }
; #pragma unroll
;                 for (int r = 0; r < 4; ++r) { const int m = m0 + r * NGW; if (m < MTOK) {
;                     const f32x4 s0 = sv[r][0], s1 = sv[r][1], s2 = sv[r][2];
;                     const float r_ssd = rsqrtf((((s0.x + s0.y) + (s0.z + s0.w)) + ((s1.x + s1.y) + (s1.z + s1.w))) * (1.f / 512.f) + EPS);
;                     const float r_att = rsqrtf(((s2.x + s2.y) + (s2.z + s2.w)) * (1.f / 256.f) + EPS);
;                     float v[8]; unpack8(yv[r][0], v);
; #pragma unroll
;                     for (int i = 0; i < 8; ++i) v[i] = v[i] * r_ssd * nwA[i];
;                     *(u32x4*)(ycat + (size_t)m * DM + colA) = pack8(v);
;                     if (lane < 32) { unpack8(yv[r][1], v);
; #pragma unroll
;                         for (int i = 0; i < 8; ++i) v[i] = v[i] * r_att * nwB[i];
;                         *(u32x4*)(ycat + (size_t)m * DM + colB) = pack8(v); } } }
	v_mul_f32_e32 v144, s62, v144
	v_mul_f32_e32 v145, s62, v145
	v_mul_f32_e32 v146, s62, v146
	v_mul_f32_e32 v147, s62, v147
	v_mul_f32_e32 v148, s62, v148
	v_mul_f32_e32 v149, s62, v149
	v_mul_f32_e32 v142, v142, v118
	v_mul_f32_e32 v143, v143, v119
	v_mul_f32_e32 v144, v144, v120
	v_mul_f32_e32 v145, v145, v121
	v_mul_f32_e32 v146, v146, v122
	v_mul_f32_e32 v147, v147, v123
	v_mul_f32_e32 v148, v148, v124
	v_mul_f32_e32 v149, v149, v125
	v_cvt_pk_bf16_f32 v150, v142, v143
	v_cvt_pk_bf16_f32 v151, v144, v145
	v_cvt_pk_bf16_f32 v152, v146, v147
	v_cvt_pk_bf16_f32 v153, v148, v149
	global_store_dwordx4 v169, v[150:153], s[6:7] offset:0
	s_nop 1
	v_add_u32_e32 v169, 6144, v117
	v_lshlrev_b32_e32 v142, 16, v182
	v_and_b32_e32 v143, 0xffff0000, v182
	v_lshlrev_b32_e32 v144, 16, v183
	v_and_b32_e32 v145, 0xffff0000, v183
	v_lshlrev_b32_e32 v146, 16, v184
	v_and_b32_e32 v147, 0xffff0000, v184
	v_lshlrev_b32_e32 v148, 16, v185
	v_and_b32_e32 v149, 0xffff0000, v185
	v_mul_f32_e32 v142, s63, v142
	v_mul_f32_e32 v143, s63, v143
	v_mul_f32_e32 v144, s63, v144
	v_mul_f32_e32 v145, s63, v145
	v_mul_f32_e32 v146, s63, v146
	v_mul_f32_e32 v147, s63, v147
	v_mul_f32_e32 v148, s63, v148
	v_mul_f32_e32 v149, s63, v149
	v_mul_f32_e32 v142, v142, v118
	v_mul_f32_e32 v143, v143, v119
	v_mul_f32_e32 v144, v144, v120
	v_mul_f32_e32 v145, v145, v121
	v_mul_f32_e32 v146, v146, v122
	v_mul_f32_e32 v147, v147, v123
	v_mul_f32_e32 v148, v148, v124
	v_mul_f32_e32 v149, v149, v125
	v_cvt_pk_bf16_f32 v150, v142, v143
	v_cvt_pk_bf16_f32 v151, v144, v145
	v_cvt_pk_bf16_f32 v152, v146, v147
	v_cvt_pk_bf16_f32 v153, v148, v149
	global_store_dwordx4 v169, v[150:153], s[6:7] offset:0
	s_nop 1
	v_add_u32_e32 v169, 8192, v117
	global_load_dwordx4 v[170:173], v169, s[4:5]
	v_add_u32_e32 v169, 10240, v117
	global_load_dwordx4 v[174:177], v169, s[4:5]
	v_add_u32_e32 v169, 12288, v117
	global_load_dwordx4 v[178:181], v169, s[4:5]
	v_add_u32_e32 v169, 14336, v117
	global_load_dwordx4 v[182:185], v169, s[4:5]
	s_waitcnt vmcnt(0)
	v_add_u32_e32 v169, 8192, v117
	v_lshlrev_b32_e32 v142, 16, v170
	v_and_b32_e32 v143, 0xffff0000, v170
	v_lshlrev_b32_e32 v144, 16, v171
	v_and_b32_e32 v145, 0xffff0000, v171
	v_lshlrev_b32_e32 v146, 16, v172
	v_and_b32_e32 v147, 0xffff0000, v172
	v_lshlrev_b32_e32 v148, 16, v173
	v_and_b32_e32 v149, 0xffff0000, v173
	v_mul_f32_e32 v142, s64, v142
	v_mul_f32_e32 v143, s64, v143
	v_mul_f32_e32 v144, s64, v144
	v_mul_f32_e32 v145, s64, v145
	v_mul_f32_e32 v146, s64, v146
	v_mul_f32_e32 v147, s64, v147
	v_mul_f32_e32 v148, s64, v148
	v_mul_f32_e32 v149, s64, v149
	v_mul_f32_e32 v142, v142, v118
	v_mul_f32_e32 v143, v143, v119
	v_mul_f32_e32 v144, v144, v120
	v_mul_f32_e32 v145, v145, v121
	v_mul_f32_e32 v146, v146, v122
	v_mul_f32_e32 v147, v147, v123
	v_mul_f32_e32 v148, v148, v124
	v_mul_f32_e32 v149, v149, v125
	v_cvt_pk_bf16_f32 v150, v142, v143
	v_cvt_pk_bf16_f32 v151, v144, v145
	v_cvt_pk_bf16_f32 v152, v146, v147
	v_cvt_pk_bf16_f32 v153, v148, v149
	global_store_dwordx4 v169, v[150:153], s[6:7] offset:0
	s_nop 1
	v_add_u32_e32 v169, 10240, v117
	v_lshlrev_b32_e32 v142, 16, v174
	v_and_b32_e32 v143, 0xffff0000, v174
	v_lshlrev_b32_e32 v144, 16, v175
	v_and_b32_e32 v145, 0xffff0000, v175
	v_lshlrev_b32_e32 v146, 16, v176
	v_and_b32_e32 v147, 0xffff0000, v176
	v_lshlrev_b32_e32 v148, 16, v177
	v_and_b32_e32 v149, 0xffff0000, v177
	v_mul_f32_e32 v142, s65, v142
	v_mul_f32_e32 v143, s65, v143
	v_mul_f32_e32 v144, s65, v144
	v_mul_f32_e32 v145, s65, v145
	v_mul_f32_e32 v146, s65, v146
	v_mul_f32_e32 v147, s65, v147
	v_mul_f32_e32 v148, s65, v148
	v_mul_f32_e32 v149, s65, v149
	v_mul_f32_e32 v142, v142, v118
	v_mul_f32_e32 v143, v143, v119
	v_mul_f32_e32 v144, v144, v120
	v_mul_f32_e32 v145, v145, v121
	v_mul_f32_e32 v146, v146, v122
	v_mul_f32_e32 v147, v147, v123
	v_mul_f32_e32 v148, v148, v124
	v_mul_f32_e32 v149, v149, v125
	v_cvt_pk_bf16_f32 v150, v142, v143
	v_cvt_pk_bf16_f32 v151, v144, v145
	v_cvt_pk_bf16_f32 v152, v146, v147
	v_cvt_pk_bf16_f32 v153, v148, v149
	global_store_dwordx4 v169, v[150:153], s[6:7] offset:0
	s_nop 1
	v_add_u32_e32 v169, 12288, v117
	v_lshlrev_b32_e32 v142, 16, v178
	v_and_b32_e32 v143, 0xffff0000, v178
	v_lshlrev_b32_e32 v144, 16, v179
	v_and_b32_e32 v145, 0xffff0000, v179
	v_lshlrev_b32_e32 v146, 16, v180
	v_and_b32_e32 v147, 0xffff0000, v180
	v_lshlrev_b32_e32 v148, 16, v181
	v_and_b32_e32 v149, 0xffff0000, v181
	v_mul_f32_e32 v142, s66, v142
	v_mul_f32_e32 v143, s66, v143
	v_mul_f32_e32 v144, s66, v144
	v_mul_f32_e32 v145, s66, v145
	v_mul_f32_e32 v146, s66, v146
	v_mul_f32_e32 v147, s66, v147
	v_mul_f32_e32 v148, s66, v148
	v_mul_f32_e32 v149, s66, v149
	v_mul_f32_e32 v142, v142, v118
	v_mul_f32_e32 v143, v143, v119
	v_mul_f32_e32 v144, v144, v120
	v_mul_f32_e32 v145, v145, v121
	v_mul_f32_e32 v146, v146, v122
	v_mul_f32_e32 v147, v147, v123
	v_mul_f32_e32 v148, v148, v124
	v_mul_f32_e32 v149, v149, v125
	v_cvt_pk_bf16_f32 v150, v142, v143
	v_cvt_pk_bf16_f32 v151, v144, v145
	v_cvt_pk_bf16_f32 v152, v146, v147
	v_cvt_pk_bf16_f32 v153, v148, v149
	global_store_dwordx4 v169, v[150:153], s[6:7] offset:0
	s_nop 1
	v_add_u32_e32 v169, 14336, v117
	v_lshlrev_b32_e32 v142, 16, v182
	v_and_b32_e32 v143, 0xffff0000, v182
	v_lshlrev_b32_e32 v144, 16, v183
	v_and_b32_e32 v145, 0xffff0000, v183
	v_lshlrev_b32_e32 v146, 16, v184
	v_and_b32_e32 v147, 0xffff0000, v184
	v_lshlrev_b32_e32 v148, 16, v185
	v_and_b32_e32 v149, 0xffff0000, v185
	v_mul_f32_e32 v142, s67, v142
	v_mul_f32_e32 v143, s67, v143
	v_mul_f32_e32 v144, s67, v144
	v_mul_f32_e32 v145, s67, v145
	v_mul_f32_e32 v146, s67, v146
	v_mul_f32_e32 v147, s67, v147
	v_mul_f32_e32 v148, s67, v148
	v_mul_f32_e32 v149, s67, v149
	v_mul_f32_e32 v142, v142, v118
	v_mul_f32_e32 v143, v143, v119
	v_mul_f32_e32 v144, v144, v120
	v_mul_f32_e32 v145, v145, v121
	v_mul_f32_e32 v146, v146, v122
	v_mul_f32_e32 v147, v147, v123
	v_mul_f32_e32 v148, v148, v124
	v_mul_f32_e32 v149, v149, v125
	v_cvt_pk_bf16_f32 v150, v142, v143
	v_cvt_pk_bf16_f32 v151, v144, v145
	v_cvt_pk_bf16_f32 v152, v146, v147
	v_cvt_pk_bf16_f32 v153, v148, v149
	global_store_dwordx4 v169, v[150:153], s[6:7] offset:0
	s_nop 1
	v_add_u32_e32 v169, 16384, v117
	global_load_dwordx4 v[170:173], v169, s[4:5]
	v_add_u32_e32 v169, 18432, v117
	global_load_dwordx4 v[174:177], v169, s[4:5]
	v_add_u32_e32 v169, 20480, v117
	global_load_dwordx4 v[178:181], v169, s[4:5]
	v_add_u32_e32 v169, 22528, v117
	global_load_dwordx4 v[182:185], v169, s[4:5]
	s_waitcnt vmcnt(0)
; DI u32x4 pack8(const float (&v)[8]) { u32x4 r; r.x = pk2(v[0], v[1]); r.y = pk2(v[2], v[3]); r.z = pk2(v[4], v[5]); r.w = pk2(v[6], v[7]); return r; }
; #define PHASE_IDS() const int tid = opaque_tid(), lane = tid & 63, r16 = lane & 15, q4 = lane >> 4; (void)r16; (void)q4; (void)tid
; __global__ void __launch_bounds__(512, 2) fwd_megakernel(Args args) {
;     ...
;             for (int m0 = gw; m0 < MTOK; m0 += 4 * NGW) {
;                 PHASE_IDS();
;                 f32x4 sv[4][3]; u32x4 yv[4][2];
;                 const int colA = lane * 8, colB = 512 + lane * 8;
; #pragma unroll
;                 for (int r = 0; r < 4; ++r) { const int m = min(m0 + r * NGW, MTOK - 1);
;                     sv[r][0] = *(const f32x4*)(mss_g + (size_t)m * 4); sv[r][1] = *(const f32x4*)(mss_g + ((size_t)MTOK + m) * 4); sv[r][2] = (f32x4){mss_a[m], mss_a[(size_t)MTOK + m], mss_a[(size_t)2 * MTOK + m], mss_a[(size_t)3 * MTOK + m]};
;                     yv[r][0] = *(const u32x4*)(Yg + (size_t)m * DM + colA); yv[r][1] = *(const u32x4*)(Yg + (size_t)m * DM + 512 + (lane & 31) * 8); }
;                 float nwA[8], nwB[8];
;                 { const float* p = args.in[12] + layer * 512 + colA;
; #pragma unroll
;                   for (int i = 0; i < 8; ++i) nwA[i] = p[i];
;                   const float* q = args.in[15] + layer * 256 + (lane & 31) * 8;
; #pragma unroll
;                   for (int i = 0; i < 8; ++i) nwB[i] = q[i]; }
; #pragma unroll
;                 for (int r = 0; r < 4; ++r) { const int m = m0 + r * NGW; if (m < MTOK) {
;                     const f32x4 s0 = sv[r][0], s1 = sv[r][1], s2 = sv[r][2];
;                     const float r_ssd = rsqrtf((((s0.x + s0.y) + (s0.z + s0.w)) + ((s1.x + s1.y) + (s1.z + s1.w))) * (1.f / 512.f) + EPS);
;                     const float r_att = rsqrtf(((s2.x + s2.y) + (s2.z + s2.w)) * (1.f / 256.f) + EPS);
;                     float v[8]; unpack8(yv[r][0], v);
; #pragma unroll
;                     for (int i = 0; i < 8; ++i) v[i] = v[i] * r_ssd * nwA[i];
;                     *(u32x4*)(ycat + (size_t)m * DM + colA) = pack8(v);
;                     if (lane < 32) { unpack8(yv[r][1], v);
; #pragma unroll
;                         for (int i = 0; i < 8; ++i) v[i] = v[i] * r_att * nwB[i];
;                         *(u32x4*)(ycat + (size_t)m * DM + colB) = pack8(v); } } }
	v_add_u32_e32 v169, 16384, v117
	v_lshlrev_b32_e32 v142, 16, v170
	v_and_b32_e32 v143, 0xffff0000, v170
	v_lshlrev_b32_e32 v144, 16, v171
	v_and_b32_e32 v145, 0xffff0000, v171
	v_lshlrev_b32_e32 v146, 16, v172
	v_and_b32_e32 v147, 0xffff0000, v172
	v_lshlrev_b32_e32 v148, 16, v173
	v_and_b32_e32 v149, 0xffff0000, v173
	v_mul_f32_e32 v142, s68, v142
	v_mul_f32_e32 v143, s68, v143
	v_mul_f32_e32 v144, s68, v144
	v_mul_f32_e32 v145, s68, v145
	v_mul_f32_e32 v146, s68, v146
	v_mul_f32_e32 v147, s68, v147
	v_mul_f32_e32 v148, s68, v148
	v_mul_f32_e32 v149, s68, v149
	v_mul_f32_e32 v142, v142, v118
	v_mul_f32_e32 v143, v143, v119
	v_mul_f32_e32 v144, v144, v120
	v_mul_f32_e32 v145, v145, v121
	v_mul_f32_e32 v146, v146, v122
	v_mul_f32_e32 v147, v147, v123
	v_mul_f32_e32 v148, v148, v124
	v_mul_f32_e32 v149, v149, v125
	v_cvt_pk_bf16_f32 v150, v142, v143
	v_cvt_pk_bf16_f32 v151, v144, v145
	v_cvt_pk_bf16_f32 v152, v146, v147
	v_cvt_pk_bf16_f32 v153, v148, v149
	global_store_dwordx4 v169, v[150:153], s[6:7] offset:0
	s_nop 1
	v_add_u32_e32 v169, 18432, v117
	v_lshlrev_b32_e32 v142, 16, v174
	v_and_b32_e32 v143, 0xffff0000, v174
	v_lshlrev_b32_e32 v144, 16, v175
	v_and_b32_e32 v145, 0xffff0000, v175
	v_lshlrev_b32_e32 v146, 16, v176
	v_and_b32_e32 v147, 0xffff0000, v176
	v_lshlrev_b32_e32 v148, 16, v177
	v_and_b32_e32 v149, 0xffff0000, v177
	v_mul_f32_e32 v142, s69, v142
	v_mul_f32_e32 v143, s69, v143
	v_mul_f32_e32 v144, s69, v144
	v_mul_f32_e32 v145, s69, v145
	v_mul_f32_e32 v146, s69, v146
	v_mul_f32_e32 v147, s69, v147
	v_mul_f32_e32 v148, s69, v148
	v_mul_f32_e32 v149, s69, v149
	v_mul_f32_e32 v142, v142, v118
	v_mul_f32_e32 v143, v143, v119
	v_mul_f32_e32 v144, v144, v120
	v_mul_f32_e32 v145, v145, v121
	v_mul_f32_e32 v146, v146, v122
	v_mul_f32_e32 v147, v147, v123
	v_mul_f32_e32 v148, v148, v124
	v_mul_f32_e32 v149, v149, v125
	v_cvt_pk_bf16_f32 v150, v142, v143
	v_cvt_pk_bf16_f32 v151, v144, v145
	v_cvt_pk_bf16_f32 v152, v146, v147
	v_cvt_pk_bf16_f32 v153, v148, v149
	global_store_dwordx4 v169, v[150:153], s[6:7] offset:0
	s_nop 1
	v_add_u32_e32 v169, 20480, v117
	v_lshlrev_b32_e32 v142, 16, v178
	v_and_b32_e32 v143, 0xffff0000, v178
	v_lshlrev_b32_e32 v144, 16, v179
	v_and_b32_e32 v145, 0xffff0000, v179
	v_lshlrev_b32_e32 v146, 16, v180
	v_and_b32_e32 v147, 0xffff0000, v180
	v_lshlrev_b32_e32 v148, 16, v181
	v_and_b32_e32 v149, 0xffff0000, v181
	v_mul_f32_e32 v142, s70, v142
	v_mul_f32_e32 v143, s70, v143
	v_mul_f32_e32 v144, s70, v144
	v_mul_f32_e32 v145, s70, v145
	v_mul_f32_e32 v146, s70, v146
	v_mul_f32_e32 v147, s70, v147
	v_mul_f32_e32 v148, s70, v148
	v_mul_f32_e32 v149, s70, v149
	v_mul_f32_e32 v142, v142, v118
	v_mul_f32_e32 v143, v143, v119
	v_mul_f32_e32 v144, v144, v120
	v_mul_f32_e32 v145, v145, v121
	v_mul_f32_e32 v146, v146, v122
	v_mul_f32_e32 v147, v147, v123
	v_mul_f32_e32 v148, v148, v124
	v_mul_f32_e32 v149, v149, v125
	v_cvt_pk_bf16_f32 v150, v142, v143
	v_cvt_pk_bf16_f32 v151, v144, v145
	v_cvt_pk_bf16_f32 v152, v146, v147
	v_cvt_pk_bf16_f32 v153, v148, v149
	global_store_dwordx4 v169, v[150:153], s[6:7] offset:0
	s_nop 1
	v_add_u32_e32 v169, 22528, v117
	v_lshlrev_b32_e32 v142, 16, v182
	v_and_b32_e32 v143, 0xffff0000, v182
	v_lshlrev_b32_e32 v144, 16, v183
	v_and_b32_e32 v145, 0xffff0000, v183
	v_lshlrev_b32_e32 v146, 16, v184
	v_and_b32_e32 v147, 0xffff0000, v184
	v_lshlrev_b32_e32 v148, 16, v185
	v_and_b32_e32 v149, 0xffff0000, v185
	v_mul_f32_e32 v142, s71, v142
	v_mul_f32_e32 v143, s71, v143
	v_mul_f32_e32 v144, s71, v144
	v_mul_f32_e32 v145, s71, v145
	v_mul_f32_e32 v146, s71, v146
	v_mul_f32_e32 v147, s71, v147
	v_mul_f32_e32 v148, s71, v148
	v_mul_f32_e32 v149, s71, v149
	v_mul_f32_e32 v142, v142, v118
	v_mul_f32_e32 v143, v143, v119
	v_mul_f32_e32 v144, v144, v120
	v_mul_f32_e32 v145, v145, v121
	v_mul_f32_e32 v146, v146, v122
	v_mul_f32_e32 v147, v147, v123
	v_mul_f32_e32 v148, v148, v124
	v_mul_f32_e32 v149, v149, v125
	v_cvt_pk_bf16_f32 v150, v142, v143
	v_cvt_pk_bf16_f32 v151, v144, v145
	v_cvt_pk_bf16_f32 v152, v146, v147
	v_cvt_pk_bf16_f32 v153, v148, v149
	global_store_dwordx4 v169, v[150:153], s[6:7] offset:0
	s_nop 1
	v_add_u32_e32 v169, 24576, v117
	global_load_dwordx4 v[170:173], v169, s[4:5]
	v_add_u32_e32 v169, 26624, v117
	global_load_dwordx4 v[174:177], v169, s[4:5]
	v_add_u32_e32 v169, 28672, v117
	global_load_dwordx4 v[178:181], v169, s[4:5]
	v_add_u32_e32 v169, 30720, v117
	global_load_dwordx4 v[182:185], v169, s[4:5]
	s_waitcnt vmcnt(0)
; DI u32x4 pack8(const float (&v)[8]) { u32x4 r; r.x = pk2(v[0], v[1]); r.y = pk2(v[2], v[3]); r.z = pk2(v[4], v[5]); r.w = pk2(v[6], v[7]); return r; }
; #define PHASE_IDS() const int tid = opaque_tid(), lane = tid & 63, r16 = lane & 15, q4 = lane >> 4; (void)r16; (void)q4; (void)tid
; __global__ void __launch_bounds__(512, 2) fwd_megakernel(Args args) {
;     ...
;             for (int m0 = gw; m0 < MTOK; m0 += 4 * NGW) {
;                 PHASE_IDS();
;                 f32x4 sv[4][3]; u32x4 yv[4][2];
;                 const int colA = lane * 8, colB = 512 + lane * 8;
; #pragma unroll
;                 for (int r = 0; r < 4; ++r) { const int m = min(m0 + r * NGW, MTOK - 1);
;                     sv[r][0] = *(const f32x4*)(mss_g + (size_t)m * 4); sv[r][1] = *(const f32x4*)(mss_g + ((size_t)MTOK + m) * 4); sv[r][2] = (f32x4){mss_a[m], mss_a[(size_t)MTOK + m], mss_a[(size_t)2 * MTOK + m], mss_a[(size_t)3 * MTOK + m]};
;                     yv[r][0] = *(const u32x4*)(Yg + (size_t)m * DM + colA); yv[r][1] = *(const u32x4*)(Yg + (size_t)m * DM + 512 + (lane & 31) * 8); }
;                 float nwA[8], nwB[8];
;                 { const float* p = args.in[12] + layer * 512 + colA;
; #pragma unroll
;                   for (int i = 0; i < 8; ++i) nwA[i] = p[i];
;                   const float* q = args.in[15] + layer * 256 + (lane & 31) * 8;
; #pragma unroll
;                   for (int i = 0; i < 8; ++i) nwB[i] = q[i]; }
; #pragma unroll
;                 for (int r = 0; r < 4; ++r) { const int m = m0 + r * NGW; if (m < MTOK) {
;                     const f32x4 s0 = sv[r][0], s1 = sv[r][1], s2 = sv[r][2];
;                     const float r_ssd = rsqrtf((((s0.x + s0.y) + (s0.z + s0.w)) + ((s1.x + s1.y) + (s1.z + s1.w))) * (1.f / 512.f) + EPS);
;                     const float r_att = rsqrtf(((s2.x + s2.y) + (s2.z + s2.w)) * (1.f / 256.f) + EPS);
;                     float v[8]; unpack8(yv[r][0], v);
; #pragma unroll
;                     for (int i = 0; i < 8; ++i) v[i] = v[i] * r_ssd * nwA[i];
;                     *(u32x4*)(ycat + (size_t)m * DM + colA) = pack8(v);
;                     if (lane < 32) { unpack8(yv[r][1], v);
; #pragma unroll
;                         for (int i = 0; i < 8; ++i) v[i] = v[i] * r_att * nwB[i];
;                         *(u32x4*)(ycat + (size_t)m * DM + colB) = pack8(v); } } }
	v_add_u32_e32 v169, 24576, v117
	v_lshlrev_b32_e32 v142, 16, v170
	v_and_b32_e32 v143, 0xffff0000, v170
	v_lshlrev_b32_e32 v144, 16, v171
	v_and_b32_e32 v145, 0xffff0000, v171
	v_lshlrev_b32_e32 v146, 16, v172
	v_and_b32_e32 v147, 0xffff0000, v172
	v_lshlrev_b32_e32 v148, 16, v173
	v_and_b32_e32 v149, 0xffff0000, v173
	v_mul_f32_e32 v142, s72, v142
	v_mul_f32_e32 v143, s72, v143
	v_mul_f32_e32 v144, s72, v144
	v_mul_f32_e32 v145, s72, v145
	v_mul_f32_e32 v146, s72, v146
	v_mul_f32_e32 v147, s72, v147
	v_mul_f32_e32 v148, s72, v148
	v_mul_f32_e32 v149, s72, v149
	v_mul_f32_e32 v142, v142, v118
	v_mul_f32_e32 v143, v143, v119
	v_mul_f32_e32 v144, v144, v120
	v_mul_f32_e32 v145, v145, v121
	v_mul_f32_e32 v146, v146, v122
	v_mul_f32_e32 v147, v147, v123
	v_mul_f32_e32 v148, v148, v124
	v_mul_f32_e32 v149, v149, v125
	v_cvt_pk_bf16_f32 v150, v142, v143
	v_cvt_pk_bf16_f32 v151, v144, v145
	v_cvt_pk_bf16_f32 v152, v146, v147
	v_cvt_pk_bf16_f32 v153, v148, v149
	global_store_dwordx4 v169, v[150:153], s[6:7] offset:0
	s_nop 1
	v_add_u32_e32 v169, 26624, v117
	v_lshlrev_b32_e32 v142, 16, v174
	v_and_b32_e32 v143, 0xffff0000, v174
	v_lshlrev_b32_e32 v144, 16, v175
	v_and_b32_e32 v145, 0xffff0000, v175
	v_lshlrev_b32_e32 v146, 16, v176
	v_and_b32_e32 v147, 0xffff0000, v176
	v_lshlrev_b32_e32 v148, 16, v177
	v_and_b32_e32 v149, 0xffff0000, v177
	v_mul_f32_e32 v142, s73, v142
	v_mul_f32_e32 v143, s73, v143
	v_mul_f32_e32 v144, s73, v144
	v_mul_f32_e32 v145, s73, v145
	v_mul_f32_e32 v146, s73, v146
	v_mul_f32_e32 v147, s73, v147
	v_mul_f32_e32 v148, s73, v148
	v_mul_f32_e32 v149, s73, v149
	v_mul_f32_e32 v142, v142, v118
	v_mul_f32_e32 v143, v143, v119
	v_mul_f32_e32 v144, v144, v120
	v_mul_f32_e32 v145, v145, v121
	v_mul_f32_e32 v146, v146, v122
	v_mul_f32_e32 v147, v147, v123
	v_mul_f32_e32 v148, v148, v124
	v_mul_f32_e32 v149, v149, v125
	v_cvt_pk_bf16_f32 v150, v142, v143
	v_cvt_pk_bf16_f32 v151, v144, v145
	v_cvt_pk_bf16_f32 v152, v146, v147
	v_cvt_pk_bf16_f32 v153, v148, v149
	global_store_dwordx4 v169, v[150:153], s[6:7] offset:0
	s_nop 1
	v_add_u32_e32 v169, 28672, v117
	v_lshlrev_b32_e32 v142, 16, v178
	v_and_b32_e32 v143, 0xffff0000, v178
	v_lshlrev_b32_e32 v144, 16, v179
	v_and_b32_e32 v145, 0xffff0000, v179
	v_lshlrev_b32_e32 v146, 16, v180
	v_and_b32_e32 v147, 0xffff0000, v180
	v_lshlrev_b32_e32 v148, 16, v181
	v_and_b32_e32 v149, 0xffff0000, v181
	v_mul_f32_e32 v142, s74, v142
	v_mul_f32_e32 v143, s74, v143
	v_mul_f32_e32 v144, s74, v144
	v_mul_f32_e32 v145, s74, v145
	v_mul_f32_e32 v146, s74, v146
	v_mul_f32_e32 v147, s74, v147
	v_mul_f32_e32 v148, s74, v148
	v_mul_f32_e32 v149, s74, v149
	v_mul_f32_e32 v142, v142, v118
	v_mul_f32_e32 v143, v143, v119
	v_mul_f32_e32 v144, v144, v120
	v_mul_f32_e32 v145, v145, v121
	v_mul_f32_e32 v146, v146, v122
	v_mul_f32_e32 v147, v147, v123
	v_mul_f32_e32 v148, v148, v124
	v_mul_f32_e32 v149, v149, v125
	v_cvt_pk_bf16_f32 v150, v142, v143
	v_cvt_pk_bf16_f32 v151, v144, v145
	v_cvt_pk_bf16_f32 v152, v146, v147
	v_cvt_pk_bf16_f32 v153, v148, v149
	global_store_dwordx4 v169, v[150:153], s[6:7] offset:0
	s_nop 1
	v_add_u32_e32 v169, 30720, v117
	v_lshlrev_b32_e32 v142, 16, v182
	v_and_b32_e32 v143, 0xffff0000, v182
	v_lshlrev_b32_e32 v144, 16, v183
	v_and_b32_e32 v145, 0xffff0000, v183
	v_lshlrev_b32_e32 v146, 16, v184
	v_and_b32_e32 v147, 0xffff0000, v184
	v_lshlrev_b32_e32 v148, 16, v185
	v_and_b32_e32 v149, 0xffff0000, v185
	v_mul_f32_e32 v142, s75, v142
	v_mul_f32_e32 v143, s75, v143
	v_mul_f32_e32 v144, s75, v144
	v_mul_f32_e32 v145, s75, v145
	v_mul_f32_e32 v146, s75, v146
	v_mul_f32_e32 v147, s75, v147
	v_mul_f32_e32 v148, s75, v148
	v_mul_f32_e32 v149, s75, v149
	v_mul_f32_e32 v142, v142, v118
	v_mul_f32_e32 v143, v143, v119
	v_mul_f32_e32 v144, v144, v120
	v_mul_f32_e32 v145, v145, v121
	v_mul_f32_e32 v146, v146, v122
	v_mul_f32_e32 v147, v147, v123
	v_mul_f32_e32 v148, v148, v124
	v_mul_f32_e32 v149, v149, v125
	v_cvt_pk_bf16_f32 v150, v142, v143
	v_cvt_pk_bf16_f32 v151, v144, v145
	v_cvt_pk_bf16_f32 v152, v146, v147
	v_cvt_pk_bf16_f32 v153, v148, v149
	global_store_dwordx4 v169, v[150:153], s[6:7] offset:0
	s_nop 1
	v_lshrrev_b32_e32 v162, 5, v116
	v_and_b32_e32 v164, 31, v116
	v_lshlrev_b32_e32 v164, 4, v164
	v_lshl_add_u32 v164, v162, 11, v164
	v_add_u32_e32 v164, 0x400, v164
	v_add_u32_e32 v169, 0, v164
	global_load_dwordx4 v[170:173], v169, s[4:5]
	v_add_u32_e32 v169, 4096, v164
	global_load_dwordx4 v[174:177], v169, s[4:5]
	v_add_u32_e32 v169, 8192, v164
	global_load_dwordx4 v[178:181], v169, s[4:5]
	v_add_u32_e32 v169, 12288, v164
	global_load_dwordx4 v[182:185], v169, s[4:5]
	v_add_u32_e32 v163, 0, v162
	v_lshlrev_b32_e32 v163, 2, v163
	ds_bpermute_b32 v168, v163, v160
	s_waitcnt vmcnt(0) lgkmcnt(0)
	v_add_u32_e32 v169, 0, v164
	v_lshlrev_b32_e32 v142, 16, v170
	v_and_b32_e32 v143, 0xffff0000, v170
	v_lshlrev_b32_e32 v144, 16, v171
	v_and_b32_e32 v145, 0xffff0000, v171
	v_lshlrev_b32_e32 v146, 16, v172
	v_and_b32_e32 v147, 0xffff0000, v172
	v_lshlrev_b32_e32 v148, 16, v173
	v_and_b32_e32 v149, 0xffff0000, v173
	v_mul_f32_e32 v142, v142, v168
	v_mul_f32_e32 v143, v143, v168
	v_mul_f32_e32 v144, v144, v168
	v_mul_f32_e32 v145, v145, v168
	v_mul_f32_e32 v146, v146, v168
	v_mul_f32_e32 v147, v147, v168
	v_mul_f32_e32 v148, v148, v168
	v_mul_f32_e32 v149, v149, v168
	v_mul_f32_e32 v142, v142, v126
	v_mul_f32_e32 v143, v143, v127
	v_mul_f32_e32 v144, v144, v128
	v_mul_f32_e32 v145, v145, v129
	v_mul_f32_e32 v146, v146, v130
	v_mul_f32_e32 v147, v147, v131
	v_mul_f32_e32 v148, v148, v132
	v_mul_f32_e32 v149, v149, v133
	v_cvt_pk_bf16_f32 v150, v142, v143
	v_cvt_pk_bf16_f32 v151, v144, v145
	v_cvt_pk_bf16_f32 v152, v146, v147
	v_cvt_pk_bf16_f32 v153, v148, v149
	global_store_dwordx4 v169, v[150:153], s[6:7] offset:0
	s_nop 1
	v_add_u32_e32 v163, 2, v162
	v_lshlrev_b32_e32 v163, 2, v163
	ds_bpermute_b32 v168, v163, v160
	s_waitcnt lgkmcnt(0)
; DI u32x4 pack8(const float (&v)[8]) { u32x4 r; r.x = pk2(v[0], v[1]); r.y = pk2(v[2], v[3]); r.z = pk2(v[4], v[5]); r.w = pk2(v[6], v[7]); return r; }
; #define PHASE_IDS() const int tid = opaque_tid(), lane = tid & 63, r16 = lane & 15, q4 = lane >> 4; (void)r16; (void)q4; (void)tid
; __global__ void __launch_bounds__(512, 2) fwd_megakernel(Args args) {
;     ...
;             for (int m0 = gw; m0 < MTOK; m0 += 4 * NGW) {
;                 PHASE_IDS();
;                 f32x4 sv[4][3]; u32x4 yv[4][2];
;                 const int colA = lane * 8, colB = 512 + lane * 8;
; #pragma unroll
;                 for (int r = 0; r < 4; ++r) { const int m = min(m0 + r * NGW, MTOK - 1);
;                     sv[r][0] = *(const f32x4*)(mss_g + (size_t)m * 4); sv[r][1] = *(const f32x4*)(mss_g + ((size_t)MTOK + m) * 4); sv[r][2] = (f32x4){mss_a[m], mss_a[(size_t)MTOK + m], mss_a[(size_t)2 * MTOK + m], mss_a[(size_t)3 * MTOK + m]};
;                     yv[r][0] = *(const u32x4*)(Yg + (size_t)m * DM + colA); yv[r][1] = *(const u32x4*)(Yg + (size_t)m * DM + 512 + (lane & 31) * 8); }
;                 float nwA[8], nwB[8];
;                 { const float* p = args.in[12] + layer * 512 + colA;
; #pragma unroll
;                   for (int i = 0; i < 8; ++i) nwA[i] = p[i];
;                   const float* q = args.in[15] + layer * 256 + (lane & 31) * 8;
; #pragma unroll
;                   for (int i = 0; i < 8; ++i) nwB[i] = q[i]; }
; #pragma unroll
;                 for (int r = 0; r < 4; ++r) { const int m = m0 + r * NGW; if (m < MTOK) {
;                     const f32x4 s0 = sv[r][0], s1 = sv[r][1], s2 = sv[r][2];
;                     const float r_ssd = rsqrtf((((s0.x + s0.y) + (s0.z + s0.w)) + ((s1.x + s1.y) + (s1.z + s1.w))) * (1.f / 512.f) + EPS);
;                     const float r_att = rsqrtf(((s2.x + s2.y) + (s2.z + s2.w)) * (1.f / 256.f) + EPS);
;                     float v[8]; unpack8(yv[r][0], v);
; #pragma unroll
;                     for (int i = 0; i < 8; ++i) v[i] = v[i] * r_ssd * nwA[i];
;                     *(u32x4*)(ycat + (size_t)m * DM + colA) = pack8(v);
;                     if (lane < 32) { unpack8(yv[r][1], v);
; #pragma unroll
;                         for (int i = 0; i < 8; ++i) v[i] = v[i] * r_att * nwB[i];
;                         *(u32x4*)(ycat + (size_t)m * DM + colB) = pack8(v); } } }
	v_add_u32_e32 v169, 4096, v164
	v_lshlrev_b32_e32 v142, 16, v174
	v_and_b32_e32 v143, 0xffff0000, v174
	v_lshlrev_b32_e32 v144, 16, v175
	v_and_b32_e32 v145, 0xffff0000, v175
	v_lshlrev_b32_e32 v146, 16, v176
	v_and_b32_e32 v147, 0xffff0000, v176
	v_lshlrev_b32_e32 v148, 16, v177
	v_and_b32_e32 v149, 0xffff0000, v177
	v_mul_f32_e32 v142, v142, v168
	v_mul_f32_e32 v143, v143, v168
	v_mul_f32_e32 v144, v144, v168
	v_mul_f32_e32 v145, v145, v168
	v_mul_f32_e32 v146, v146, v168
	v_mul_f32_e32 v147, v147, v168
	v_mul_f32_e32 v148, v148, v168
	v_mul_f32_e32 v149, v149, v168
	v_mul_f32_e32 v142, v142, v126
	v_mul_f32_e32 v143, v143, v127
	v_mul_f32_e32 v144, v144, v128
	v_mul_f32_e32 v145, v145, v129
	v_mul_f32_e32 v146, v146, v130
	v_mul_f32_e32 v147, v147, v131
	v_mul_f32_e32 v148, v148, v132
	v_mul_f32_e32 v149, v149, v133
	v_cvt_pk_bf16_f32 v150, v142, v143
	v_cvt_pk_bf16_f32 v151, v144, v145
	v_cvt_pk_bf16_f32 v152, v146, v147
	v_cvt_pk_bf16_f32 v153, v148, v149
	global_store_dwordx4 v169, v[150:153], s[6:7] offset:0
	s_nop 1
	v_add_u32_e32 v163, 4, v162
	v_lshlrev_b32_e32 v163, 2, v163
	ds_bpermute_b32 v168, v163, v160
	s_waitcnt lgkmcnt(0)
	v_add_u32_e32 v169, 8192, v164
	v_lshlrev_b32_e32 v142, 16, v178
	v_and_b32_e32 v143, 0xffff0000, v178
	v_lshlrev_b32_e32 v144, 16, v179
	v_and_b32_e32 v145, 0xffff0000, v179
	v_lshlrev_b32_e32 v146, 16, v180
	v_and_b32_e32 v147, 0xffff0000, v180
	v_lshlrev_b32_e32 v148, 16, v181
	v_and_b32_e32 v149, 0xffff0000, v181
	v_mul_f32_e32 v142, v142, v168
	v_mul_f32_e32 v143, v143, v168
	v_mul_f32_e32 v144, v144, v168
	v_mul_f32_e32 v145, v145, v168
	v_mul_f32_e32 v146, v146, v168
	v_mul_f32_e32 v147, v147, v168
	v_mul_f32_e32 v148, v148, v168
	v_mul_f32_e32 v149, v149, v168
	v_mul_f32_e32 v142, v142, v126
	v_mul_f32_e32 v143, v143, v127
	v_mul_f32_e32 v144, v144, v128
	v_mul_f32_e32 v145, v145, v129
	v_mul_f32_e32 v146, v146, v130
	v_mul_f32_e32 v147, v147, v131
	v_mul_f32_e32 v148, v148, v132
	v_mul_f32_e32 v149, v149, v133
	v_cvt_pk_bf16_f32 v150, v142, v143
	v_cvt_pk_bf16_f32 v151, v144, v145
	v_cvt_pk_bf16_f32 v152, v146, v147
	v_cvt_pk_bf16_f32 v153, v148, v149
	global_store_dwordx4 v169, v[150:153], s[6:7] offset:0
	s_nop 1
	v_add_u32_e32 v163, 6, v162
	v_lshlrev_b32_e32 v163, 2, v163
	ds_bpermute_b32 v168, v163, v160
	s_waitcnt lgkmcnt(0)
	v_add_u32_e32 v169, 12288, v164
	v_lshlrev_b32_e32 v142, 16, v182
	v_and_b32_e32 v143, 0xffff0000, v182
	v_lshlrev_b32_e32 v144, 16, v183
	v_and_b32_e32 v145, 0xffff0000, v183
	v_lshlrev_b32_e32 v146, 16, v184
	v_and_b32_e32 v147, 0xffff0000, v184
	v_lshlrev_b32_e32 v148, 16, v185
	v_and_b32_e32 v149, 0xffff0000, v185
	v_mul_f32_e32 v142, v142, v168
	v_mul_f32_e32 v143, v143, v168
	v_mul_f32_e32 v144, v144, v168
	v_mul_f32_e32 v145, v145, v168
	v_mul_f32_e32 v146, v146, v168
	v_mul_f32_e32 v147, v147, v168
	v_mul_f32_e32 v148, v148, v168
	v_mul_f32_e32 v149, v149, v168
	v_mul_f32_e32 v142, v142, v126
	v_mul_f32_e32 v143, v143, v127
	v_mul_f32_e32 v144, v144, v128
	v_mul_f32_e32 v145, v145, v129
	v_mul_f32_e32 v146, v146, v130
	v_mul_f32_e32 v147, v147, v131
	v_mul_f32_e32 v148, v148, v132
	v_mul_f32_e32 v149, v149, v133
	v_cvt_pk_bf16_f32 v150, v142, v143
	v_cvt_pk_bf16_f32 v151, v144, v145
	v_cvt_pk_bf16_f32 v152, v146, v147
	v_cvt_pk_bf16_f32 v153, v148, v149
	global_store_dwordx4 v169, v[150:153], s[6:7] offset:0
	s_nop 1
	v_add_u32_e32 v169, 16384, v164
	global_load_dwordx4 v[170:173], v169, s[4:5]
	v_add_u32_e32 v169, 20480, v164
	global_load_dwordx4 v[174:177], v169, s[4:5]
	v_add_u32_e32 v169, 24576, v164
	global_load_dwordx4 v[178:181], v169, s[4:5]
	v_add_u32_e32 v169, 28672, v164
	global_load_dwordx4 v[182:185], v169, s[4:5]
	v_add_u32_e32 v163, 8, v162
	v_lshlrev_b32_e32 v163, 2, v163
	ds_bpermute_b32 v168, v163, v160
	s_waitcnt vmcnt(0) lgkmcnt(0)
	v_add_u32_e32 v169, 16384, v164
	v_lshlrev_b32_e32 v142, 16, v170
	v_and_b32_e32 v143, 0xffff0000, v170
	v_lshlrev_b32_e32 v144, 16, v171
	v_and_b32_e32 v145, 0xffff0000, v171
	v_lshlrev_b32_e32 v146, 16, v172
	v_and_b32_e32 v147, 0xffff0000, v172
	v_lshlrev_b32_e32 v148, 16, v173
	v_and_b32_e32 v149, 0xffff0000, v173
	v_mul_f32_e32 v142, v142, v168
	v_mul_f32_e32 v143, v143, v168
	v_mul_f32_e32 v144, v144, v168
	v_mul_f32_e32 v145, v145, v168
	v_mul_f32_e32 v146, v146, v168
	v_mul_f32_e32 v147, v147, v168
	v_mul_f32_e32 v148, v148, v168
	v_mul_f32_e32 v149, v149, v168
	v_mul_f32_e32 v142, v142, v126
	v_mul_f32_e32 v143, v143, v127
	v_mul_f32_e32 v144, v144, v128
	v_mul_f32_e32 v145, v145, v129
	v_mul_f32_e32 v146, v146, v130
	v_mul_f32_e32 v147, v147, v131
	v_mul_f32_e32 v148, v148, v132
	v_mul_f32_e32 v149, v149, v133
	v_cvt_pk_bf16_f32 v150, v142, v143
	v_cvt_pk_bf16_f32 v151, v144, v145
	v_cvt_pk_bf16_f32 v152, v146, v147
	v_cvt_pk_bf16_f32 v153, v148, v149
	global_store_dwordx4 v169, v[150:153], s[6:7] offset:0
	s_nop 1
	v_add_u32_e32 v163, 10, v162
	v_lshlrev_b32_e32 v163, 2, v163
	ds_bpermute_b32 v168, v163, v160
	s_waitcnt lgkmcnt(0)
; DI u32x4 pack8(const float (&v)[8]) { u32x4 r; r.x = pk2(v[0], v[1]); r.y = pk2(v[2], v[3]); r.z = pk2(v[4], v[5]); r.w = pk2(v[6], v[7]); return r; }
; #define PHASE_IDS() const int tid = opaque_tid(), lane = tid & 63, r16 = lane & 15, q4 = lane >> 4; (void)r16; (void)q4; (void)tid
; __global__ void __launch_bounds__(512, 2) fwd_megakernel(Args args) {
;     ...
;             for (int m0 = gw; m0 < MTOK; m0 += 4 * NGW) {
;                 PHASE_IDS();
;                 f32x4 sv[4][3]; u32x4 yv[4][2];
;                 const int colA = lane * 8, colB = 512 + lane * 8;
; #pragma unroll
;                 for (int r = 0; r < 4; ++r) { const int m = min(m0 + r * NGW, MTOK - 1);
;                     sv[r][0] = *(const f32x4*)(mss_g + (size_t)m * 4); sv[r][1] = *(const f32x4*)(mss_g + ((size_t)MTOK + m) * 4); sv[r][2] = (f32x4){mss_a[m], mss_a[(size_t)MTOK + m], mss_a[(size_t)2 * MTOK + m], mss_a[(size_t)3 * MTOK + m]};
;                     yv[r][0] = *(const u32x4*)(Yg + (size_t)m * DM + colA); yv[r][1] = *(const u32x4*)(Yg + (size_t)m * DM + 512 + (lane & 31) * 8); }
;                 float nwA[8], nwB[8];
;                 { const float* p = args.in[12] + layer * 512 + colA;
; #pragma unroll
;                   for (int i = 0; i < 8; ++i) nwA[i] = p[i];
;                   const float* q = args.in[15] + layer * 256 + (lane & 31) * 8;
; #pragma unroll
;                   for (int i = 0; i < 8; ++i) nwB[i] = q[i]; }
; #pragma unroll
;                 for (int r = 0; r < 4; ++r) { const int m = m0 + r * NGW; if (m < MTOK) {
;                     const f32x4 s0 = sv[r][0], s1 = sv[r][1], s2 = sv[r][2];
;                     const float r_ssd = rsqrtf((((s0.x + s0.y) + (s0.z + s0.w)) + ((s1.x + s1.y) + (s1.z + s1.w))) * (1.f / 512.f) + EPS);
;                     const float r_att = rsqrtf(((s2.x + s2.y) + (s2.z + s2.w)) * (1.f / 256.f) + EPS);
;                     float v[8]; unpack8(yv[r][0], v);
; #pragma unroll
;                     for (int i = 0; i < 8; ++i) v[i] = v[i] * r_ssd * nwA[i];
;                     *(u32x4*)(ycat + (size_t)m * DM + colA) = pack8(v);
;                     if (lane < 32) { unpack8(yv[r][1], v);
; #pragma unroll
;                         for (int i = 0; i < 8; ++i) v[i] = v[i] * r_att * nwB[i];
;                         *(u32x4*)(ycat + (size_t)m * DM + colB) = pack8(v); } } }
	v_add_u32_e32 v169, 20480, v164
	v_lshlrev_b32_e32 v142, 16, v174
	v_and_b32_e32 v143, 0xffff0000, v174
	v_lshlrev_b32_e32 v144, 16, v175
	v_and_b32_e32 v145, 0xffff0000, v175
	v_lshlrev_b32_e32 v146, 16, v176
	v_and_b32_e32 v147, 0xffff0000, v176
	v_lshlrev_b32_e32 v148, 16, v177
	v_and_b32_e32 v149, 0xffff0000, v177
	v_mul_f32_e32 v142, v142, v168
	v_mul_f32_e32 v143, v143, v168
	v_mul_f32_e32 v144, v144, v168
	v_mul_f32_e32 v145, v145, v168
	v_mul_f32_e32 v146, v146, v168
	v_mul_f32_e32 v147, v147, v168
	v_mul_f32_e32 v148, v148, v168
	v_mul_f32_e32 v149, v149, v168
	v_mul_f32_e32 v142, v142, v126
	v_mul_f32_e32 v143, v143, v127
	v_mul_f32_e32 v144, v144, v128
	v_mul_f32_e32 v145, v145, v129
	v_mul_f32_e32 v146, v146, v130
	v_mul_f32_e32 v147, v147, v131
	v_mul_f32_e32 v148, v148, v132
	v_mul_f32_e32 v149, v149, v133
	v_cvt_pk_bf16_f32 v150, v142, v143
	v_cvt_pk_bf16_f32 v151, v144, v145
	v_cvt_pk_bf16_f32 v152, v146, v147
	v_cvt_pk_bf16_f32 v153, v148, v149
	global_store_dwordx4 v169, v[150:153], s[6:7] offset:0
	s_nop 1
	v_add_u32_e32 v163, 12, v162
	v_lshlrev_b32_e32 v163, 2, v163
	ds_bpermute_b32 v168, v163, v160
	s_waitcnt lgkmcnt(0)
	v_add_u32_e32 v169, 24576, v164
	v_lshlrev_b32_e32 v142, 16, v178
	v_and_b32_e32 v143, 0xffff0000, v178
	v_lshlrev_b32_e32 v144, 16, v179
	v_and_b32_e32 v145, 0xffff0000, v179
	v_lshlrev_b32_e32 v146, 16, v180
	v_and_b32_e32 v147, 0xffff0000, v180
	v_lshlrev_b32_e32 v148, 16, v181
	v_and_b32_e32 v149, 0xffff0000, v181
	v_mul_f32_e32 v142, v142, v168
	v_mul_f32_e32 v143, v143, v168
	v_mul_f32_e32 v144, v144, v168
	v_mul_f32_e32 v145, v145, v168
	v_mul_f32_e32 v146, v146, v168
	v_mul_f32_e32 v147, v147, v168
	v_mul_f32_e32 v148, v148, v168
	v_mul_f32_e32 v149, v149, v168
	v_mul_f32_e32 v142, v142, v126
	v_mul_f32_e32 v143, v143, v127
	v_mul_f32_e32 v144, v144, v128
	v_mul_f32_e32 v145, v145, v129
	v_mul_f32_e32 v146, v146, v130
	v_mul_f32_e32 v147, v147, v131
	v_mul_f32_e32 v148, v148, v132
	v_mul_f32_e32 v149, v149, v133
	v_cvt_pk_bf16_f32 v150, v142, v143
	v_cvt_pk_bf16_f32 v151, v144, v145
	v_cvt_pk_bf16_f32 v152, v146, v147
	v_cvt_pk_bf16_f32 v153, v148, v149
	global_store_dwordx4 v169, v[150:153], s[6:7] offset:0
	s_nop 1
	v_add_u32_e32 v163, 14, v162
	v_lshlrev_b32_e32 v163, 2, v163
	ds_bpermute_b32 v168, v163, v160
	s_waitcnt lgkmcnt(0)
	v_add_u32_e32 v169, 28672, v164
	v_lshlrev_b32_e32 v142, 16, v182
	v_and_b32_e32 v143, 0xffff0000, v182
	v_lshlrev_b32_e32 v144, 16, v183
	v_and_b32_e32 v145, 0xffff0000, v183
	v_lshlrev_b32_e32 v146, 16, v184
	v_and_b32_e32 v147, 0xffff0000, v184
	v_lshlrev_b32_e32 v148, 16, v185
	v_and_b32_e32 v149, 0xffff0000, v185
	v_mul_f32_e32 v142, v142, v168
	v_mul_f32_e32 v143, v143, v168
	v_mul_f32_e32 v144, v144, v168
	v_mul_f32_e32 v145, v145, v168
	v_mul_f32_e32 v146, v146, v168
	v_mul_f32_e32 v147, v147, v168
	v_mul_f32_e32 v148, v148, v168
	v_mul_f32_e32 v149, v149, v168
	v_mul_f32_e32 v142, v142, v126
	v_mul_f32_e32 v143, v143, v127
	v_mul_f32_e32 v144, v144, v128
	v_mul_f32_e32 v145, v145, v129
	v_mul_f32_e32 v146, v146, v130
	v_mul_f32_e32 v147, v147, v131
	v_mul_f32_e32 v148, v148, v132
	v_mul_f32_e32 v149, v149, v133
	v_cvt_pk_bf16_f32 v150, v142, v143
	v_cvt_pk_bf16_f32 v151, v144, v145
	v_cvt_pk_bf16_f32 v152, v146, v147
	v_cvt_pk_bf16_f32 v153, v148, v149
	global_store_dwordx4 v169, v[150:153], s[6:7] offset:0
	s_nop 1
	v_readlane_b32 s76, v251, 57
	v_readlane_b32 s77, v251, 58
	v_readlane_b32 s52, v251, 61
	v_readlane_b32 s78, v253, 42
	v_readlane_b32 s53, v251, 62
	v_readlane_b32 s72, v251, 59
	v_readlane_b32 s79, v253, 43
	v_readlane_b32 s51, v251, 63
	v_readlane_b32 s54, v251, 0
	v_readlane_b32 s73, v251, 60
	s_mul_i32 s55, s82, 24
	v_readlane_b32 s74, v253, 27
	v_readlane_b32 s75, v253, 28
	v_readlane_b32 s79, v253, 29
	v_readlane_b32 s83, v253, 30
	v_readlane_b32 s53, v253, 26
	s_nop 4
	s_branch .LBB0_1129
